# XCD-hierarchical grid barrier (per-XCD arrival + generation words, only 8 leaders poll the global counter); attention schedule PRE=8
# speedup vs baseline: 1.1168x; 1.0348x over previous
; DEV void grid_barrier(unsigned* cnt, const unsigned target, const int tid) {
;     asm volatile("s_waitcnt vmcnt(0)" ::: "memory");
;     __syncthreads();
;     if (tid == 0) {
;         __builtin_amdgcn_fence(__ATOMIC_RELEASE, "agent");
;         __hip_atomic_fetch_add(cnt, 1u, __ATOMIC_RELAXED, __HIP_MEMORY_SCOPE_AGENT);
;         while (__hip_atomic_load(cnt, __ATOMIC_RELAXED, __HIP_MEMORY_SCOPE_AGENT) < target) __builtin_amdgcn_s_sleep(28);
;         __builtin_amdgcn_fence(__ATOMIC_ACQUIRE, "agent");
;         asm volatile("s_waitcnt vmcnt(0)" ::: "memory");
;     }
;     __syncthreads();
; }
; template <int LO, int HI>
; DEV void run_phases(LAS unsigned char* lds, const int ph_lo, const int ph_hi, const int G, const int wave0, unsigned& nbar) {
;     ...
;             if (ph_lo < ph) { ++nbar; grid_barrier((unsigned*)(ws + WS_BAR), nbar * (unsigned)G, tid); }
.LBB0_198:
	s_or_b64 exec, exec, s[12:13]
	v_readlane_b32 s2, v251, 12
	v_readlane_b32 s3, v251, 13
	s_andn2_b64 vcc, exec, s[2:3]
	s_cbranch_vccnz .LBB0_206
	s_waitcnt vmcnt(0)
	v_readlane_b32 s2, v251, 5
	s_add_i32 s2, s2, 1
	v_cmp_eq_u32_e32 vcc, 0, v155
	v_writelane_b32 v251, s2, 5
	s_barrier
	s_and_saveexec_b64 s[2:3], vcc
	s_cbranch_execz .LBB0_205
	buffer_wbl2 sc1
	s_waitcnt vmcnt(0)
	v_readlane_b32 s4, v251, 2
	v_readlane_b32 s5, v251, 3
	v_readlane_b32 s6, v251, 1
	v_readlane_b32 s7, v251, 5
	s_getreg_b32 s12, hwreg(HW_REG_XCC_ID, 0, 4)
	s_load_dwordx2 s[4:5], s[4:5], 0x110
	s_lshr_b32 s6, s6, 3
	s_mul_i32 s6, s6, s7
	s_lshl_b32 s13, s7, 3
	s_lshl_b32 s12, s12, 2
	s_add_u32 s12, s12, 0x40
	v_mov_b32_e32 v3, 1
	v_mov_b32_e32 v2, s12
	v_mov_b32_e32 v5, 0
	s_waitcnt lgkmcnt(0)
	s_add_u32 s4, s4, 0x300000
	s_addc_u32 s5, s5, 0
	global_atomic_add v4, v2, v3, s[4:5] sc0
	s_waitcnt vmcnt(0)
	v_add_u32_e32 v4, 1, v4
	v_cmp_eq_u32_e32 vcc, s6, v4
	s_cbranch_vccz .Lgb0_follow
	global_atomic_add v5, v3, s[4:5]
.Lgb0_ptop:
	global_load_dword v4, v5, s[4:5] sc1
	s_waitcnt vmcnt(0)
	v_cmp_gt_u32_e32 vcc, s13, v4
	s_cbranch_vccz .Lgb0_tdone
	s_sleep 28
	s_branch .Lgb0_ptop
.Lgb0_tdone:
	v_mov_b32_e32 v4, s7
	global_store_dword v2, v4, s[4:5] offset:64
	s_branch .Lgb0_done
.Lgb0_follow:
	global_load_dword v4, v2, s[4:5] offset:64 sc1
	s_waitcnt vmcnt(0)
	v_cmp_gt_u32_e32 vcc, s7, v4
	s_cbranch_vccz .Lgb0_done
	s_sleep 8
	s_branch .Lgb0_follow
.Lgb0_done:
.LBB0_204:
	buffer_inv sc1
	s_waitcnt vmcnt(0)

; DEV void grid_barrier(unsigned* cnt, const unsigned target, const int tid) {
;     asm volatile("s_waitcnt vmcnt(0)" ::: "memory");
;     __syncthreads();
;     if (tid == 0) {
;         __builtin_amdgcn_fence(__ATOMIC_RELEASE, "agent");
;         __hip_atomic_fetch_add(cnt, 1u, __ATOMIC_RELAXED, __HIP_MEMORY_SCOPE_AGENT);
;         while (__hip_atomic_load(cnt, __ATOMIC_RELAXED, __HIP_MEMORY_SCOPE_AGENT) < target) __builtin_amdgcn_s_sleep(28);
;         __builtin_amdgcn_fence(__ATOMIC_ACQUIRE, "agent");
;         asm volatile("s_waitcnt vmcnt(0)" ::: "memory");
;     }
;     __syncthreads();
; }
; template <int LO, int HI>
; DEV void run_phases(LAS unsigned char* lds, const int ph_lo, const int ph_hi, const int G, const int wave0, unsigned& nbar) {
;     ...
;         if (ph + 1 < ph_hi) { __syncthreads(); if (HI == 1) cg::this_grid().sync(); else { ++nbar; grid_barrier((unsigned*)(ws + WS_BAR), nbar * (unsigned)G, tid); } }
.LBB0_1358:
	v_readlane_b32 s2, v251, 7
	s_add_i32 s0, s77, 1
	v_readlane_b32 s3, v251, 8
	s_cmp_ge_i32 s0, s3
	s_cbranch_scc1 .LBB0_1366
	s_barrier
	s_waitcnt vmcnt(0)
	v_readlane_b32 s0, v251, 5
	s_add_i32 s0, s0, 1
	v_cmp_eq_u32_e32 vcc, 0, v130
	v_writelane_b32 v251, s0, 5
	s_barrier
	s_and_saveexec_b64 s[0:1], vcc
	s_cbranch_execz .LBB0_1365
	buffer_wbl2 sc1
	s_waitcnt vmcnt(0)
	v_readlane_b32 s2, v251, 2
	v_readlane_b32 s3, v251, 3
	v_readlane_b32 s4, v251, 1
	v_readlane_b32 s5, v251, 5
	s_getreg_b32 s6, hwreg(HW_REG_XCC_ID, 0, 4)
	s_load_dwordx2 s[2:3], s[2:3], 0x110
	s_lshr_b32 s4, s4, 3
	s_mul_i32 s4, s4, s5
	s_lshl_b32 s7, s5, 3
	s_lshl_b32 s6, s6, 2
	s_add_u32 s6, s6, 0x40
	v_mov_b32_e32 v3, 1
	v_mov_b32_e32 v2, s6
	v_mov_b32_e32 v5, 0
	s_waitcnt lgkmcnt(0)
	s_add_u32 s2, s2, 0x300000
	s_addc_u32 s3, s3, 0
	global_atomic_add v4, v2, v3, s[2:3] sc0
	s_waitcnt vmcnt(0)
	v_add_u32_e32 v4, 1, v4
	v_cmp_eq_u32_e32 vcc, s4, v4
	s_cbranch_vccz .Lgb1_follow
	global_atomic_add v5, v3, s[2:3]
.Lgb1_ptop:
	global_load_dword v4, v5, s[2:3] sc1
	s_waitcnt vmcnt(0)
	v_cmp_gt_u32_e32 vcc, s7, v4
	s_cbranch_vccz .Lgb1_tdone
	s_sleep 28
	s_branch .Lgb1_ptop
.Lgb1_tdone:
	v_mov_b32_e32 v4, s5
	global_store_dword v2, v4, s[2:3] offset:64
	s_branch .Lgb1_done
.Lgb1_follow:
	global_load_dword v4, v2, s[2:3] offset:64 sc1
	s_waitcnt vmcnt(0)
	v_cmp_gt_u32_e32 vcc, s5, v4
	s_cbranch_vccz .Lgb1_done
	s_sleep 8
	s_branch .Lgb1_follow

; DEV void grid_barrier(unsigned* cnt, const unsigned target, const int tid) {
;     asm volatile("s_waitcnt vmcnt(0)" ::: "memory");
;     __syncthreads();
;     if (tid == 0) {
;         __builtin_amdgcn_fence(__ATOMIC_RELEASE, "agent");
;         __hip_atomic_fetch_add(cnt, 1u, __ATOMIC_RELAXED, __HIP_MEMORY_SCOPE_AGENT);
; template <int LO, int HI>
; DEV void run_phases(LAS unsigned char* lds, const int ph_lo, const int ph_hi, const int G, const int wave0, unsigned& nbar) {
;     ...
;             if (ph_lo < ph) { ++nbar; grid_barrier((unsigned*)(ws + WS_BAR), nbar * (unsigned)G, tid); }
.LBB0_1396:
	s_or_b64 exec, exec, s[0:1]
	v_readlane_b32 s0, v251, 20
	v_readlane_b32 s1, v251, 21
	s_andn2_b64 vcc, exec, s[0:1]
	s_cbranch_vccnz .LBB0_1404
	s_waitcnt vmcnt(0)
	v_readlane_b32 s0, v251, 5
	s_add_i32 s0, s0, 1
	v_cmp_eq_u32_e32 vcc, 0, v172
	v_writelane_b32 v251, s0, 5
	s_barrier
	s_and_saveexec_b64 s[0:1], vcc
	s_cbranch_execz .LBB0_1403
	buffer_wbl2 sc1
	s_waitcnt vmcnt(0)
	v_readlane_b32 s2, v251, 2
	v_readlane_b32 s3, v251, 3
	v_readlane_b32 s4, v251, 1
	v_readlane_b32 s5, v251, 5
	s_getreg_b32 s6, hwreg(HW_REG_XCC_ID, 0, 4)
	s_load_dwordx2 s[2:3], s[2:3], 0x110
	s_lshr_b32 s4, s4, 3
	s_mul_i32 s4, s4, s5
	s_lshl_b32 s7, s5, 3
	s_lshl_b32 s6, s6, 2
	s_add_u32 s6, s6, 0x40
	v_mov_b32_e32 v3, 1
	v_mov_b32_e32 v2, s6
	v_mov_b32_e32 v5, 0
	s_waitcnt lgkmcnt(0)
	s_add_u32 s2, s2, 0x300000
	s_addc_u32 s3, s3, 0
	global_atomic_add v4, v2, v3, s[2:3] sc0
	s_waitcnt vmcnt(0)
	v_add_u32_e32 v4, 1, v4
	v_cmp_eq_u32_e32 vcc, s4, v4
	s_cbranch_vccz .Lgb2_follow
	global_atomic_add v5, v3, s[2:3]

; DEV void pvh(f32x16* o, int vb, bf16x8 pa, bf16x8 pb) {
;     s16x4 lo[4], hi[4];
; #pragma unroll
;     for (int d0 = 0; d0 < 2; ++d0)
; #pragma unroll
;         for (int kk = 0; kk < 2; ++kk) {
;             asm volatile("ds_read_b64_tr_b16 %0,%1 offset:%c2" : "=&v"(lo[d0 * 2 + kk]) : "v"(vb), "i"(d0 * 4096 + kk * 1024) : "memory");
;             asm volatile("ds_read_b64_tr_b16 %0,%1 offset:%c2" : "=&v"(hi[d0 * 2 + kk]) : "v"(vb), "i"(d0 * 4096 + kk * 1024 + 512) : "memory"); }
;     asm volatile("s_waitcnt lgkmcnt(0)" ::: "memory"); __builtin_amdgcn_sched_barrier(0);
;     ...
;     o[0] = __builtin_amdgcn_mfma_f32_32x32x16_bf16(pa, PKV(0), o[0], 0, 0, 0);
;     o[1] = __builtin_amdgcn_mfma_f32_32x32x16_bf16(pa, PKV(2), o[1], 0, 0, 0);
;     o[0] = __builtin_amdgcn_mfma_f32_32x32x16_bf16(pb, PKV(1), o[0], 0, 0, 0);
;     o[1] = __builtin_amdgcn_mfma_f32_32x32x16_bf16(pb, PKV(3), o[1], 0, 0, 0);
;     ...
; }
.Lat_k2_5:
	s_add_u32 s12, s12, 0x30000
	s_addc_u32 s13, s13, 0
	s_add_i32 m0, s22, 0x13000
	s_nop 0
	global_load_lds_dwordx4 v145, s[14:15]
	s_add_u32 s14, s14, 0x20000
	s_addc_u32 s15, s15, 0
	v_exp_f32_e32 v48, v48
	v_exp_f32_e32 v49, v49
	v_exp_f32_e32 v50, v50
	v_exp_f32_e32 v51, v51
	v_mov_b32_e32 v176, v48
	v_mov_b32_e32 v177, v49
	v_cvt_pk_bf16_f32 v48, v48, v49
	v_add_f32_e32 v176, v50, v176
	s_waitcnt lgkmcnt(8)
	v_mfma_f32_32x32x16_bf16 v[80:95], v[196:199], v[110:113], v[224:239]
	ds_read_b128 v[196:199], v194 offset:26624
	ds_read_b64_tr_b16 v[240:241], v139 offset:1024
	ds_read_b64_tr_b16 v[242:243], v139 offset:1536
	v_add_f32_e32 v177, v51, v177
	v_cvt_pk_bf16_f32 v49, v50, v51
	v_exp_f32_e32 v52, v52
	v_exp_f32_e32 v53, v53
	v_mfma_f32_32x32x16_bf16 v[64:79], v[200:203], v[110:113], v[224:239]
	ds_read_b128 v[200:203], v194 offset:27136
	ds_read_b64_tr_b16 v[122:123], v139 offset:5120
	ds_read_b64_tr_b16 v[124:125], v139 offset:5632
	v_exp_f32_e32 v54, v54
	v_exp_f32_e32 v55, v55
	v_add_f32_e32 v176, v52, v176
	v_add_f32_e32 v177, v53, v177
	s_waitcnt lgkmcnt(12)
	v_mfma_f32_32x32x16_bf16 v[80:95], v[204:207], v[106:109], v[80:95]
	ds_read_b128 v[204:207], v194 offset:28672
	v_cvt_pk_bf16_f32 v50, v52, v53
	v_add_f32_e32 v176, v54, v176
	v_add_f32_e32 v177, v55, v177
	v_cvt_pk_bf16_f32 v51, v54, v55
	v_mfma_f32_32x32x16_bf16 v[64:79], v[208:211], v[106:109], v[64:79]
	ds_read_b128 v[208:211], v194 offset:29184
	v_exp_f32_e32 v56, v56
	v_exp_f32_e32 v57, v57
	v_exp_f32_e32 v58, v58
	v_exp_f32_e32 v59, v59
	s_waitcnt lgkmcnt(8)
	v_mfma_f32_32x32x16_bf16 v[80:95], v[212:215], v[114:117], v[80:95]
	ds_read_b128 v[212:215], v194 offset:30720
	v_add_f32_e32 v176, v56, v176
	v_add_f32_e32 v177, v57, v177
	v_cvt_pk_bf16_f32 v52, v56, v57
	v_add_f32_e32 v176, v58, v176
	v_mfma_f32_32x32x16_bf16 v[0:15], v[48:51], v[220:223], v[0:15]
	ds_read_b64_tr_b16 v[220:221], v139 offset:2048
	ds_read_b64_tr_b16 v[222:223], v139 offset:2560
	v_add_f32_e32 v177, v59, v177
	v_cvt_pk_bf16_f32 v53, v58, v59
	v_exp_f32_e32 v60, v60
	v_exp_f32_e32 v61, v61
	v_mfma_f32_32x32x16_bf16 v[16:31], v[48:51], v[244:247], v[16:31]
	ds_read_b64_tr_b16 v[244:245], v139 offset:6144
	ds_read_b64_tr_b16 v[246:247], v139 offset:6656
	v_exp_f32_e32 v62, v62
	v_exp_f32_e32 v63, v63
	v_add_f32_e32 v176, v60, v176
	v_add_f32_e32 v177, v61, v177
	v_mfma_f32_32x32x16_bf16 v[64:79], v[216:219], v[114:117], v[64:79]
	ds_read_b128 v[216:219], v194 offset:31232
	v_cvt_pk_bf16_f32 v54, v60, v61
	v_add_f32_e32 v176, v62, v176
	v_add_f32_e32 v177, v63, v177
	v_cvt_pk_bf16_f32 v55, v62, v63
	s_waitcnt lgkmcnt(10)
	v_mfma_f32_32x32x16_bf16 v[80:95], v[196:199], v[118:121], v[80:95]
	v_exp_f32_e32 v32, v32
	v_exp_f32_e32 v33, v33
	v_exp_f32_e32 v34, v34
	v_exp_f32_e32 v35, v35
	v_mfma_f32_32x32x16_bf16 v[64:79], v[200:203], v[118:121], v[64:79]
	v_add_f32_e32 v176, v32, v176
	v_add_f32_e32 v177, v33, v177
	v_cvt_pk_bf16_f32 v32, v32, v33
	v_add_f32_e32 v176, v34, v176
	s_waitcnt lgkmcnt(8)
	v_mfma_f32_32x32x16_bf16 v[0:15], v[52:55], v[240:243], v[0:15]
	ds_read_b64_tr_b16 v[240:241], v139 offset:3072
	ds_read_b64_tr_b16 v[242:243], v139 offset:3584
	v_add_f32_e32 v177, v35, v177
	v_cvt_pk_bf16_f32 v33, v34, v35
	v_exp_f32_e32 v36, v36
	v_exp_f32_e32 v37, v37
	v_mfma_f32_32x32x16_bf16 v[16:31], v[52:55], v[122:125], v[16:31]
	ds_read_b64_tr_b16 v[122:123], v139 offset:7168
	ds_read_b64_tr_b16 v[124:125], v139 offset:7680
	v_exp_f32_e32 v38, v38
	v_exp_f32_e32 v39, v39
	v_add_f32_e32 v176, v36, v176
	v_add_f32_e32 v177, v37, v177
	s_waitcnt vmcnt(2)
	s_barrier
; DEV void pvh(f32x16* o, int vb, bf16x8 pa, bf16x8 pb) {
;     s16x4 lo[4], hi[4];
; #pragma unroll
;     for (int d0 = 0; d0 < 2; ++d0)
; #pragma unroll
;         for (int kk = 0; kk < 2; ++kk) {
;             asm volatile("ds_read_b64_tr_b16 %0,%1 offset:%c2" : "=&v"(lo[d0 * 2 + kk]) : "v"(vb), "i"(d0 * 4096 + kk * 1024) : "memory");
;             asm volatile("ds_read_b64_tr_b16 %0,%1 offset:%c2" : "=&v"(hi[d0 * 2 + kk]) : "v"(vb), "i"(d0 * 4096 + kk * 1024 + 512) : "memory"); }
;     asm volatile("s_waitcnt lgkmcnt(0)" ::: "memory"); __builtin_amdgcn_sched_barrier(0);
;     ...
;     o[0] = __builtin_amdgcn_mfma_f32_32x32x16_bf16(pa, PKV(0), o[0], 0, 0, 0);
;     o[1] = __builtin_amdgcn_mfma_f32_32x32x16_bf16(pa, PKV(2), o[1], 0, 0, 0);
;     o[0] = __builtin_amdgcn_mfma_f32_32x32x16_bf16(pb, PKV(1), o[0], 0, 0, 0);
;     o[1] = __builtin_amdgcn_mfma_f32_32x32x16_bf16(pb, PKV(3), o[1], 0, 0, 0);
;     ...
; }
	s_waitcnt lgkmcnt(10)
	v_mfma_f32_32x32x16_bf16 v[80:95], v[204:207], v[102:105], v[80:95]
	ds_read_b128 v[196:199], v126 offset:0
	ds_read_b128 v[200:203], v126 offset:512
	ds_read_b128 v[204:207], v126 offset:2048
	v_cvt_pk_bf16_f32 v34, v36, v37
	v_add_f32_e32 v176, v38, v176
	v_add_f32_e32 v177, v39, v177
	v_cvt_pk_bf16_f32 v35, v38, v39
	v_mfma_f32_32x32x16_bf16 v[64:79], v[208:211], v[102:105], v[64:79]
	ds_read_b128 v[208:211], v126 offset:2560
	v_exp_f32_e32 v40, v40
	v_exp_f32_e32 v41, v41
	v_exp_f32_e32 v42, v42
	v_exp_f32_e32 v43, v43
	s_waitcnt lgkmcnt(9)
	v_mfma_f32_32x32x16_bf16 v[0:15], v[32:35], v[220:223], v[0:15]
	ds_read_b64_tr_b16 v[220:221], v139 offset:20480
	ds_read_b64_tr_b16 v[222:223], v139 offset:20992
	v_add_f32_e32 v176, v40, v176
	v_add_f32_e32 v177, v41, v177
	v_cvt_pk_bf16_f32 v36, v40, v41
	v_add_f32_e32 v176, v42, v176
	v_mfma_f32_32x32x16_bf16 v[16:31], v[32:35], v[244:247], v[16:31]
	ds_read_b64_tr_b16 v[244:245], v139 offset:24576
	ds_read_b64_tr_b16 v[246:247], v139 offset:25088
	v_add_f32_e32 v177, v43, v177
	v_cvt_pk_bf16_f32 v37, v42, v43
	v_exp_f32_e32 v44, v44
	v_exp_f32_e32 v45, v45
	s_waitcnt lgkmcnt(12)
	v_mfma_f32_32x32x16_bf16 v[80:95], v[212:215], v[98:101], v[80:95]
	ds_read_b128 v[212:215], v126 offset:4096
	v_exp_f32_e32 v46, v46
	v_exp_f32_e32 v47, v47
	v_add_f32_e32 v176, v44, v176
	v_add_f32_e32 v177, v45, v177
	v_mfma_f32_32x32x16_bf16 v[64:79], v[216:219], v[98:101], v[64:79]
	ds_read_b128 v[216:219], v126 offset:4608
	v_cvt_pk_bf16_f32 v38, v44, v45
	v_add_f32_e32 v176, v46, v176
	v_add_f32_e32 v177, v47, v177
	v_cvt_pk_bf16_f32 v39, v46, v47
	s_waitcnt lgkmcnt(10)
	v_mfma_f32_32x32x16_bf16 v[0:15], v[36:39], v[240:243], v[0:15]
	v_add_f32_e32 v175, v176, v177
	v_mov_b32_e32 v178, v175
	v_add_f32_e32 v147, v147, v175
	s_nop 0
	v_mfma_f32_32x32x16_bf16 v[16:31], v[36:39], v[122:125], v[16:31]
	v_permlane32_swap_b32_e32 v175, v178
	v_add_f32_e32 v175, v175, v178
	v_cmp_lt_f32_e32 vcc, 0x43800000, v175
	s_cbranch_vccz .Lat_nr_6
	v_log_f32_e32 v175, v175
	s_nop 0
	v_max_f32_e32 v175, 0, v175
	v_exp_f32_e64 v178, -v175
	s_and_saveexec_b64 s[4:5], s[2:3]
	ds_write_b32 v143, v178 offset:40960
	s_or_b64 exec, exec, s[4:5]
	s_waitcnt lgkmcnt(0)
	v_add_u32_e32 v179, s33, v191
	v_sub_f32_e32 v224, v224, v175
	v_mul_f32_e32 v147, v147, v178
	ds_read_b128 v[48:51], v179 offset:40960
	ds_read_b128 v[52:55], v179 offset:40992
	ds_read_b128 v[56:59], v179 offset:41024
	ds_read_b128 v[60:63], v179 offset:41056
	s_waitcnt lgkmcnt(0)
	s_nop 15
	v_pk_mul_f32 v[0:1], v[0:1], v[48:49]
	v_pk_mul_f32 v[2:3], v[2:3], v[50:51]
	v_pk_mul_f32 v[4:5], v[4:5], v[52:53]
	v_pk_mul_f32 v[6:7], v[6:7], v[54:55]
	v_pk_mul_f32 v[8:9], v[8:9], v[56:57]
	v_pk_mul_f32 v[10:11], v[10:11], v[58:59]
	v_pk_mul_f32 v[12:13], v[12:13], v[60:61]
	v_pk_mul_f32 v[14:15], v[14:15], v[62:63]
	v_pk_mul_f32 v[16:17], v[16:17], v[48:49]
	v_pk_mul_f32 v[18:19], v[18:19], v[50:51]
	v_pk_mul_f32 v[20:21], v[20:21], v[52:53]
	v_pk_mul_f32 v[22:23], v[22:23], v[54:55]
	v_pk_mul_f32 v[24:25], v[24:25], v[56:57]
	v_pk_mul_f32 v[26:27], v[26:27], v[58:59]
	v_pk_mul_f32 v[28:29], v[28:29], v[60:61]
	v_pk_mul_f32 v[30:31], v[30:31], v[62:63]
	v_mov_b32_e32 v225, v224
	v_mov_b32_e32 v226, v224
	v_mov_b32_e32 v227, v224
	v_mov_b32_e32 v228, v224
	v_mov_b32_e32 v229, v224
	v_mov_b32_e32 v230, v224
	v_mov_b32_e32 v231, v224
	v_mov_b32_e32 v232, v224
	v_mov_b32_e32 v233, v224
	v_mov_b32_e32 v234, v224
	v_mov_b32_e32 v235, v224
	v_mov_b32_e32 v236, v224
	v_mov_b32_e32 v237, v224
	v_mov_b32_e32 v238, v224
	v_mov_b32_e32 v239, v224
	v_sub_f32_e32 v80, v80, v175
	v_sub_f32_e32 v81, v81, v175
	v_sub_f32_e32 v82, v82, v175
	v_sub_f32_e32 v83, v83, v175
	v_sub_f32_e32 v84, v84, v175
	v_sub_f32_e32 v85, v85, v175
	v_sub_f32_e32 v86, v86, v175
	v_sub_f32_e32 v87, v87, v175
	v_sub_f32_e32 v88, v88, v175
	v_sub_f32_e32 v89, v89, v175
	v_sub_f32_e32 v90, v90, v175
	v_sub_f32_e32 v91, v91, v175
	v_sub_f32_e32 v92, v92, v175
	v_sub_f32_e32 v93, v93, v175
	v_sub_f32_e32 v94, v94, v175
	v_sub_f32_e32 v95, v95, v175
	v_sub_f32_e32 v64, v64, v175
	v_sub_f32_e32 v65, v65, v175
	v_sub_f32_e32 v66, v66, v175
	v_sub_f32_e32 v67, v67, v175
	v_sub_f32_e32 v68, v68, v175
	v_sub_f32_e32 v69, v69, v175
	v_sub_f32_e32 v70, v70, v175
	v_sub_f32_e32 v71, v71, v175
	v_sub_f32_e32 v72, v72, v175
	v_sub_f32_e32 v73, v73, v175
	v_sub_f32_e32 v74, v74, v175
	v_sub_f32_e32 v75, v75, v175
	v_sub_f32_e32 v76, v76, v175
	v_sub_f32_e32 v77, v77, v175
	v_sub_f32_e32 v78, v78, v175
	v_sub_f32_e32 v79, v79, v175

; DEV void pvh(f32x16* o, int vb, bf16x8 pa, bf16x8 pb) {
;     s16x4 lo[4], hi[4];
; #pragma unroll
;     for (int d0 = 0; d0 < 2; ++d0)
; #pragma unroll
;         for (int kk = 0; kk < 2; ++kk) {
;             asm volatile("ds_read_b64_tr_b16 %0,%1 offset:%c2" : "=&v"(lo[d0 * 2 + kk]) : "v"(vb), "i"(d0 * 4096 + kk * 1024) : "memory");
;             asm volatile("ds_read_b64_tr_b16 %0,%1 offset:%c2" : "=&v"(hi[d0 * 2 + kk]) : "v"(vb), "i"(d0 * 4096 + kk * 1024 + 512) : "memory"); }
;     asm volatile("s_waitcnt lgkmcnt(0)" ::: "memory"); __builtin_amdgcn_sched_barrier(0);
;     ...
;     o[0] = __builtin_amdgcn_mfma_f32_32x32x16_bf16(pa, PKV(0), o[0], 0, 0, 0);
;     o[1] = __builtin_amdgcn_mfma_f32_32x32x16_bf16(pa, PKV(2), o[1], 0, 0, 0);
;     o[0] = __builtin_amdgcn_mfma_f32_32x32x16_bf16(pb, PKV(1), o[0], 0, 0, 0);
;     o[1] = __builtin_amdgcn_mfma_f32_32x32x16_bf16(pb, PKV(3), o[1], 0, 0, 0);
;     ...
; }
.Lat_k2_7:
	s_add_u32 s12, s12, 0x30000
	s_addc_u32 s13, s13, 0
	s_add_i32 m0, s22, 0x18000
	s_nop 0
	global_load_lds_dwordx4 v145, s[14:15]
	s_add_u32 s14, s14, 0x20000
	s_addc_u32 s15, s15, 0
	v_exp_f32_e32 v80, v80
	v_exp_f32_e32 v81, v81
	v_exp_f32_e32 v82, v82
	v_exp_f32_e32 v83, v83
	v_mov_b32_e32 v176, v80
	v_mov_b32_e32 v177, v81
	v_cvt_pk_bf16_f32 v80, v80, v81
	v_add_f32_e32 v176, v82, v176
	s_waitcnt lgkmcnt(8)
	v_mfma_f32_32x32x16_bf16 v[48:63], v[196:199], v[110:113], v[224:239]
	ds_read_b128 v[196:199], v126 offset:6144
	ds_read_b64_tr_b16 v[240:241], v139 offset:21504
	ds_read_b64_tr_b16 v[242:243], v139 offset:22016
	v_add_f32_e32 v177, v83, v177
	v_cvt_pk_bf16_f32 v81, v82, v83
	v_exp_f32_e32 v84, v84
	v_exp_f32_e32 v85, v85
	v_mfma_f32_32x32x16_bf16 v[32:47], v[200:203], v[110:113], v[224:239]
	ds_read_b128 v[200:203], v126 offset:6656
	ds_read_b64_tr_b16 v[122:123], v139 offset:25600
	ds_read_b64_tr_b16 v[124:125], v139 offset:26112
	v_exp_f32_e32 v86, v86
	v_exp_f32_e32 v87, v87
	v_add_f32_e32 v176, v84, v176
	v_add_f32_e32 v177, v85, v177
	s_waitcnt lgkmcnt(12)
	v_mfma_f32_32x32x16_bf16 v[48:63], v[204:207], v[106:109], v[48:63]
	ds_read_b128 v[204:207], v126 offset:8192
	v_cvt_pk_bf16_f32 v82, v84, v85
	v_add_f32_e32 v176, v86, v176
	v_add_f32_e32 v177, v87, v177
	v_cvt_pk_bf16_f32 v83, v86, v87
	v_mfma_f32_32x32x16_bf16 v[32:47], v[208:211], v[106:109], v[32:47]
	ds_read_b128 v[208:211], v126 offset:8704
	v_exp_f32_e32 v88, v88
	v_exp_f32_e32 v89, v89
	v_exp_f32_e32 v90, v90
	v_exp_f32_e32 v91, v91
	s_waitcnt lgkmcnt(8)
	v_mfma_f32_32x32x16_bf16 v[48:63], v[212:215], v[114:117], v[48:63]
	ds_read_b128 v[212:215], v126 offset:10240
	v_add_f32_e32 v176, v88, v176
	v_add_f32_e32 v177, v89, v177
	v_cvt_pk_bf16_f32 v84, v88, v89
	v_add_f32_e32 v176, v90, v176
	v_mfma_f32_32x32x16_bf16 v[0:15], v[80:83], v[220:223], v[0:15]
	ds_read_b64_tr_b16 v[220:221], v139 offset:22528
	ds_read_b64_tr_b16 v[222:223], v139 offset:23040
	v_add_f32_e32 v177, v91, v177
	v_cvt_pk_bf16_f32 v85, v90, v91
	v_exp_f32_e32 v92, v92
	v_exp_f32_e32 v93, v93
	v_mfma_f32_32x32x16_bf16 v[16:31], v[80:83], v[244:247], v[16:31]
	ds_read_b64_tr_b16 v[244:245], v139 offset:26624
	ds_read_b64_tr_b16 v[246:247], v139 offset:27136
	v_exp_f32_e32 v94, v94
	v_exp_f32_e32 v95, v95
	v_add_f32_e32 v176, v92, v176
	v_add_f32_e32 v177, v93, v177
	v_mfma_f32_32x32x16_bf16 v[32:47], v[216:219], v[114:117], v[32:47]
	ds_read_b128 v[216:219], v126 offset:10752
	v_cvt_pk_bf16_f32 v86, v92, v93
	v_add_f32_e32 v176, v94, v176
	v_add_f32_e32 v177, v95, v177
	v_cvt_pk_bf16_f32 v87, v94, v95
	s_waitcnt lgkmcnt(10)
	v_mfma_f32_32x32x16_bf16 v[48:63], v[196:199], v[118:121], v[48:63]
	v_exp_f32_e32 v64, v64
	v_exp_f32_e32 v65, v65
	v_exp_f32_e32 v66, v66
	v_exp_f32_e32 v67, v67
	v_mfma_f32_32x32x16_bf16 v[32:47], v[200:203], v[118:121], v[32:47]
	v_add_f32_e32 v176, v64, v176
	v_add_f32_e32 v177, v65, v177
	v_cvt_pk_bf16_f32 v64, v64, v65
	v_add_f32_e32 v176, v66, v176
	s_waitcnt lgkmcnt(8)
	v_mfma_f32_32x32x16_bf16 v[0:15], v[84:87], v[240:243], v[0:15]
	ds_read_b64_tr_b16 v[240:241], v139 offset:23552
	ds_read_b64_tr_b16 v[242:243], v139 offset:24064
	v_add_f32_e32 v177, v67, v177
	v_cvt_pk_bf16_f32 v65, v66, v67
	v_exp_f32_e32 v68, v68
	v_exp_f32_e32 v69, v69
	v_mfma_f32_32x32x16_bf16 v[16:31], v[84:87], v[122:125], v[16:31]
	ds_read_b64_tr_b16 v[122:123], v139 offset:27648
	ds_read_b64_tr_b16 v[124:125], v139 offset:28160
	v_exp_f32_e32 v70, v70
	v_exp_f32_e32 v71, v71
	v_add_f32_e32 v176, v68, v176
	v_add_f32_e32 v177, v69, v177
	s_waitcnt vmcnt(2)
	s_barrier
; DEV void pvh(f32x16* o, int vb, bf16x8 pa, bf16x8 pb) {
;     s16x4 lo[4], hi[4];
; #pragma unroll
;     for (int d0 = 0; d0 < 2; ++d0)
; #pragma unroll
;         for (int kk = 0; kk < 2; ++kk) {
;             asm volatile("ds_read_b64_tr_b16 %0,%1 offset:%c2" : "=&v"(lo[d0 * 2 + kk]) : "v"(vb), "i"(d0 * 4096 + kk * 1024) : "memory");
;             asm volatile("ds_read_b64_tr_b16 %0,%1 offset:%c2" : "=&v"(hi[d0 * 2 + kk]) : "v"(vb), "i"(d0 * 4096 + kk * 1024 + 512) : "memory"); }
;     asm volatile("s_waitcnt lgkmcnt(0)" ::: "memory"); __builtin_amdgcn_sched_barrier(0);
;     ...
;     o[0] = __builtin_amdgcn_mfma_f32_32x32x16_bf16(pa, PKV(0), o[0], 0, 0, 0);
;     o[1] = __builtin_amdgcn_mfma_f32_32x32x16_bf16(pa, PKV(2), o[1], 0, 0, 0);
;     o[0] = __builtin_amdgcn_mfma_f32_32x32x16_bf16(pb, PKV(1), o[0], 0, 0, 0);
;     o[1] = __builtin_amdgcn_mfma_f32_32x32x16_bf16(pb, PKV(3), o[1], 0, 0, 0);
;     ...
; }
	s_waitcnt lgkmcnt(10)
	v_mfma_f32_32x32x16_bf16 v[48:63], v[204:207], v[102:105], v[48:63]
	ds_read_b128 v[196:199], v126 offset:20480
	ds_read_b128 v[200:203], v126 offset:20992
	ds_read_b128 v[204:207], v126 offset:22528
	v_cvt_pk_bf16_f32 v66, v68, v69
	v_add_f32_e32 v176, v70, v176
	v_add_f32_e32 v177, v71, v177
	v_cvt_pk_bf16_f32 v67, v70, v71
	v_mfma_f32_32x32x16_bf16 v[32:47], v[208:211], v[102:105], v[32:47]
	ds_read_b128 v[208:211], v126 offset:23040
	v_exp_f32_e32 v72, v72
	v_exp_f32_e32 v73, v73
	v_exp_f32_e32 v74, v74
	v_exp_f32_e32 v75, v75
	s_waitcnt lgkmcnt(9)
	v_mfma_f32_32x32x16_bf16 v[0:15], v[64:67], v[220:223], v[0:15]
	ds_read_b64_tr_b16 v[220:221], v127 offset:0
	ds_read_b64_tr_b16 v[222:223], v127 offset:512
	v_add_f32_e32 v176, v72, v176
	v_add_f32_e32 v177, v73, v177
	v_cvt_pk_bf16_f32 v68, v72, v73
	v_add_f32_e32 v176, v74, v176
	v_mfma_f32_32x32x16_bf16 v[16:31], v[64:67], v[244:247], v[16:31]
	ds_read_b64_tr_b16 v[244:245], v127 offset:4096
	ds_read_b64_tr_b16 v[246:247], v127 offset:4608
	v_add_f32_e32 v177, v75, v177
	v_cvt_pk_bf16_f32 v69, v74, v75
	v_exp_f32_e32 v76, v76
	v_exp_f32_e32 v77, v77
	s_waitcnt lgkmcnt(12)
	v_mfma_f32_32x32x16_bf16 v[48:63], v[212:215], v[98:101], v[48:63]
	ds_read_b128 v[212:215], v126 offset:24576
	v_exp_f32_e32 v78, v78
	v_exp_f32_e32 v79, v79
	v_add_f32_e32 v176, v76, v176
	v_add_f32_e32 v177, v77, v177
	v_mfma_f32_32x32x16_bf16 v[32:47], v[216:219], v[98:101], v[32:47]
	ds_read_b128 v[216:219], v126 offset:25088
	v_cvt_pk_bf16_f32 v70, v76, v77
	v_add_f32_e32 v176, v78, v176
	v_add_f32_e32 v177, v79, v177
	v_cvt_pk_bf16_f32 v71, v78, v79
	s_waitcnt lgkmcnt(10)
	v_mfma_f32_32x32x16_bf16 v[0:15], v[68:71], v[240:243], v[0:15]
	v_add_f32_e32 v175, v176, v177
	v_mov_b32_e32 v178, v175
	v_add_f32_e32 v147, v147, v175
	s_nop 0
	v_mfma_f32_32x32x16_bf16 v[16:31], v[68:71], v[122:125], v[16:31]
	v_permlane32_swap_b32_e32 v175, v178
	v_add_f32_e32 v175, v175, v178
	v_cmp_lt_f32_e32 vcc, 0x43800000, v175
	s_cbranch_vccz .Lat_nr_8
	v_log_f32_e32 v175, v175
	s_nop 0
	v_max_f32_e32 v175, 0, v175
	v_exp_f32_e64 v178, -v175
	s_and_saveexec_b64 s[4:5], s[2:3]
	ds_write_b32 v143, v178 offset:40960
	s_or_b64 exec, exec, s[4:5]
	s_waitcnt lgkmcnt(0)
	v_add_u32_e32 v179, s33, v191
	v_sub_f32_e32 v224, v224, v175
	v_mul_f32_e32 v147, v147, v178
	ds_read_b128 v[80:83], v179 offset:40960
	ds_read_b128 v[84:87], v179 offset:40992
	ds_read_b128 v[88:91], v179 offset:41024
	ds_read_b128 v[92:95], v179 offset:41056
	s_waitcnt lgkmcnt(0)
	s_nop 15
	v_pk_mul_f32 v[0:1], v[0:1], v[80:81]
	v_pk_mul_f32 v[2:3], v[2:3], v[82:83]
	v_pk_mul_f32 v[4:5], v[4:5], v[84:85]
	v_pk_mul_f32 v[6:7], v[6:7], v[86:87]
	v_pk_mul_f32 v[8:9], v[8:9], v[88:89]
	v_pk_mul_f32 v[10:11], v[10:11], v[90:91]
	v_pk_mul_f32 v[12:13], v[12:13], v[92:93]
	v_pk_mul_f32 v[14:15], v[14:15], v[94:95]
	v_pk_mul_f32 v[16:17], v[16:17], v[80:81]
	v_pk_mul_f32 v[18:19], v[18:19], v[82:83]
	v_pk_mul_f32 v[20:21], v[20:21], v[84:85]
	v_pk_mul_f32 v[22:23], v[22:23], v[86:87]
	v_pk_mul_f32 v[24:25], v[24:25], v[88:89]
	v_pk_mul_f32 v[26:27], v[26:27], v[90:91]
	v_pk_mul_f32 v[28:29], v[28:29], v[92:93]
	v_pk_mul_f32 v[30:31], v[30:31], v[94:95]
	v_mov_b32_e32 v225, v224
	v_mov_b32_e32 v226, v224
	v_mov_b32_e32 v227, v224
	v_mov_b32_e32 v228, v224
	v_mov_b32_e32 v229, v224
	v_mov_b32_e32 v230, v224
	v_mov_b32_e32 v231, v224
	v_mov_b32_e32 v232, v224
	v_mov_b32_e32 v233, v224
	v_mov_b32_e32 v234, v224
	v_mov_b32_e32 v235, v224
	v_mov_b32_e32 v236, v224
	v_mov_b32_e32 v237, v224
	v_mov_b32_e32 v238, v224
	v_mov_b32_e32 v239, v224
	v_sub_f32_e32 v48, v48, v175
	v_sub_f32_e32 v49, v49, v175
	v_sub_f32_e32 v50, v50, v175
	v_sub_f32_e32 v51, v51, v175
	v_sub_f32_e32 v52, v52, v175
	v_sub_f32_e32 v53, v53, v175
	v_sub_f32_e32 v54, v54, v175
	v_sub_f32_e32 v55, v55, v175
	v_sub_f32_e32 v56, v56, v175
	v_sub_f32_e32 v57, v57, v175
	v_sub_f32_e32 v58, v58, v175
	v_sub_f32_e32 v59, v59, v175
	v_sub_f32_e32 v60, v60, v175
	v_sub_f32_e32 v61, v61, v175
	v_sub_f32_e32 v62, v62, v175
	v_sub_f32_e32 v63, v63, v175
	v_sub_f32_e32 v32, v32, v175
	v_sub_f32_e32 v33, v33, v175
	v_sub_f32_e32 v34, v34, v175
	v_sub_f32_e32 v35, v35, v175
	v_sub_f32_e32 v36, v36, v175
	v_sub_f32_e32 v37, v37, v175
	v_sub_f32_e32 v38, v38, v175
	v_sub_f32_e32 v39, v39, v175
	v_sub_f32_e32 v40, v40, v175
	v_sub_f32_e32 v41, v41, v175
	v_sub_f32_e32 v42, v42, v175
	v_sub_f32_e32 v43, v43, v175
	v_sub_f32_e32 v44, v44, v175
	v_sub_f32_e32 v45, v45, v175
	v_sub_f32_e32 v46, v46, v175
	v_sub_f32_e32 v47, v47, v175

; DEV void pvh(f32x16* o, int vb, bf16x8 pa, bf16x8 pb) {
;     s16x4 lo[4], hi[4];
; #pragma unroll
;     for (int d0 = 0; d0 < 2; ++d0)
; #pragma unroll
;         for (int kk = 0; kk < 2; ++kk) {
;             asm volatile("ds_read_b64_tr_b16 %0,%1 offset:%c2" : "=&v"(lo[d0 * 2 + kk]) : "v"(vb), "i"(d0 * 4096 + kk * 1024) : "memory");
;             asm volatile("ds_read_b64_tr_b16 %0,%1 offset:%c2" : "=&v"(hi[d0 * 2 + kk]) : "v"(vb), "i"(d0 * 4096 + kk * 1024 + 512) : "memory"); }
;     asm volatile("s_waitcnt lgkmcnt(0)" ::: "memory"); __builtin_amdgcn_sched_barrier(0);
;     ...
;     o[0] = __builtin_amdgcn_mfma_f32_32x32x16_bf16(pa, PKV(0), o[0], 0, 0, 0);
;     o[1] = __builtin_amdgcn_mfma_f32_32x32x16_bf16(pa, PKV(2), o[1], 0, 0, 0);
;     o[0] = __builtin_amdgcn_mfma_f32_32x32x16_bf16(pb, PKV(1), o[0], 0, 0, 0);
;     o[1] = __builtin_amdgcn_mfma_f32_32x32x16_bf16(pb, PKV(3), o[1], 0, 0, 0);
;     ...
; }
.Lat_k2_9:
	s_add_u32 s12, s12, 0x30000
	s_addc_u32 s13, s13, 0
	s_add_i32 m0, s22, 0x3000
	s_nop 0
	global_load_lds_dwordx4 v145, s[14:15]
	s_add_u32 s14, s14, 0x20000
	s_addc_u32 s15, s15, 0
	v_exp_f32_e32 v48, v48
	v_exp_f32_e32 v49, v49
	v_exp_f32_e32 v50, v50
	v_exp_f32_e32 v51, v51
	v_mov_b32_e32 v176, v48
	v_mov_b32_e32 v177, v49
	v_cvt_pk_bf16_f32 v48, v48, v49
	v_add_f32_e32 v176, v50, v176
	s_waitcnt lgkmcnt(8)
	v_mfma_f32_32x32x16_bf16 v[80:95], v[196:199], v[110:113], v[224:239]
	ds_read_b128 v[196:199], v126 offset:26624
	ds_read_b64_tr_b16 v[240:241], v127 offset:1024
	ds_read_b64_tr_b16 v[242:243], v127 offset:1536
	v_add_f32_e32 v177, v51, v177
	v_cvt_pk_bf16_f32 v49, v50, v51
	v_exp_f32_e32 v52, v52
	v_exp_f32_e32 v53, v53
	v_mfma_f32_32x32x16_bf16 v[64:79], v[200:203], v[110:113], v[224:239]
	ds_read_b128 v[200:203], v126 offset:27136
	ds_read_b64_tr_b16 v[122:123], v127 offset:5120
	ds_read_b64_tr_b16 v[124:125], v127 offset:5632
	v_exp_f32_e32 v54, v54
	v_exp_f32_e32 v55, v55
	v_add_f32_e32 v176, v52, v176
	v_add_f32_e32 v177, v53, v177
	s_waitcnt lgkmcnt(12)
	v_mfma_f32_32x32x16_bf16 v[80:95], v[204:207], v[106:109], v[80:95]
	ds_read_b128 v[204:207], v126 offset:28672
	v_cvt_pk_bf16_f32 v50, v52, v53
	v_add_f32_e32 v176, v54, v176
	v_add_f32_e32 v177, v55, v177
	v_cvt_pk_bf16_f32 v51, v54, v55
	v_mfma_f32_32x32x16_bf16 v[64:79], v[208:211], v[106:109], v[64:79]
	ds_read_b128 v[208:211], v126 offset:29184
	v_exp_f32_e32 v56, v56
	v_exp_f32_e32 v57, v57
	v_exp_f32_e32 v58, v58
	v_exp_f32_e32 v59, v59
	s_waitcnt lgkmcnt(8)
	v_mfma_f32_32x32x16_bf16 v[80:95], v[212:215], v[114:117], v[80:95]
	ds_read_b128 v[212:215], v126 offset:30720
	v_add_f32_e32 v176, v56, v176
	v_add_f32_e32 v177, v57, v177
	v_cvt_pk_bf16_f32 v52, v56, v57
	v_add_f32_e32 v176, v58, v176
	v_mfma_f32_32x32x16_bf16 v[0:15], v[48:51], v[220:223], v[0:15]
	ds_read_b64_tr_b16 v[220:221], v127 offset:2048
	ds_read_b64_tr_b16 v[222:223], v127 offset:2560
	v_add_f32_e32 v177, v59, v177
	v_cvt_pk_bf16_f32 v53, v58, v59
	v_exp_f32_e32 v60, v60
	v_exp_f32_e32 v61, v61
	v_mfma_f32_32x32x16_bf16 v[16:31], v[48:51], v[244:247], v[16:31]
	ds_read_b64_tr_b16 v[244:245], v127 offset:6144
	ds_read_b64_tr_b16 v[246:247], v127 offset:6656
	v_exp_f32_e32 v62, v62
	v_exp_f32_e32 v63, v63
	v_add_f32_e32 v176, v60, v176
	v_add_f32_e32 v177, v61, v177
	v_mfma_f32_32x32x16_bf16 v[64:79], v[216:219], v[114:117], v[64:79]
	ds_read_b128 v[216:219], v126 offset:31232
	v_cvt_pk_bf16_f32 v54, v60, v61
	v_add_f32_e32 v176, v62, v176
	v_add_f32_e32 v177, v63, v177
	v_cvt_pk_bf16_f32 v55, v62, v63
	s_waitcnt lgkmcnt(10)
	v_mfma_f32_32x32x16_bf16 v[80:95], v[196:199], v[118:121], v[80:95]
	v_exp_f32_e32 v32, v32
	v_exp_f32_e32 v33, v33
	v_exp_f32_e32 v34, v34
	v_exp_f32_e32 v35, v35
	v_mfma_f32_32x32x16_bf16 v[64:79], v[200:203], v[118:121], v[64:79]
	v_add_f32_e32 v176, v32, v176
	v_add_f32_e32 v177, v33, v177
	v_cvt_pk_bf16_f32 v32, v32, v33
	v_add_f32_e32 v176, v34, v176
	s_waitcnt lgkmcnt(8)
	v_mfma_f32_32x32x16_bf16 v[0:15], v[52:55], v[240:243], v[0:15]
	ds_read_b64_tr_b16 v[240:241], v127 offset:3072
	ds_read_b64_tr_b16 v[242:243], v127 offset:3584
	v_add_f32_e32 v177, v35, v177
	v_cvt_pk_bf16_f32 v33, v34, v35
	v_exp_f32_e32 v36, v36
	v_exp_f32_e32 v37, v37
	v_mfma_f32_32x32x16_bf16 v[16:31], v[52:55], v[122:125], v[16:31]
	ds_read_b64_tr_b16 v[122:123], v127 offset:7168
	ds_read_b64_tr_b16 v[124:125], v127 offset:7680
	v_exp_f32_e32 v38, v38
	v_exp_f32_e32 v39, v39
	v_add_f32_e32 v176, v36, v176
	v_add_f32_e32 v177, v37, v177
	s_waitcnt vmcnt(2)
	s_barrier
; DEV void pvh(f32x16* o, int vb, bf16x8 pa, bf16x8 pb) {
;     s16x4 lo[4], hi[4];
; #pragma unroll
;     for (int d0 = 0; d0 < 2; ++d0)
; #pragma unroll
;         for (int kk = 0; kk < 2; ++kk) {
;             asm volatile("ds_read_b64_tr_b16 %0,%1 offset:%c2" : "=&v"(lo[d0 * 2 + kk]) : "v"(vb), "i"(d0 * 4096 + kk * 1024) : "memory");
;             asm volatile("ds_read_b64_tr_b16 %0,%1 offset:%c2" : "=&v"(hi[d0 * 2 + kk]) : "v"(vb), "i"(d0 * 4096 + kk * 1024 + 512) : "memory"); }
;     asm volatile("s_waitcnt lgkmcnt(0)" ::: "memory"); __builtin_amdgcn_sched_barrier(0);
;     ...
;     o[0] = __builtin_amdgcn_mfma_f32_32x32x16_bf16(pa, PKV(0), o[0], 0, 0, 0);
;     o[1] = __builtin_amdgcn_mfma_f32_32x32x16_bf16(pa, PKV(2), o[1], 0, 0, 0);
;     o[0] = __builtin_amdgcn_mfma_f32_32x32x16_bf16(pb, PKV(1), o[0], 0, 0, 0);
;     o[1] = __builtin_amdgcn_mfma_f32_32x32x16_bf16(pb, PKV(3), o[1], 0, 0, 0);
;     ...
; }
	s_waitcnt lgkmcnt(10)
	v_mfma_f32_32x32x16_bf16 v[80:95], v[204:207], v[102:105], v[80:95]
	ds_read_b128 v[196:199], v194 offset:0
	ds_read_b128 v[200:203], v194 offset:512
	ds_read_b128 v[204:207], v194 offset:2048
	v_cvt_pk_bf16_f32 v34, v36, v37
	v_add_f32_e32 v176, v38, v176
	v_add_f32_e32 v177, v39, v177
	v_cvt_pk_bf16_f32 v35, v38, v39
	v_mfma_f32_32x32x16_bf16 v[64:79], v[208:211], v[102:105], v[64:79]
	ds_read_b128 v[208:211], v194 offset:2560
	v_exp_f32_e32 v40, v40
	v_exp_f32_e32 v41, v41
	v_exp_f32_e32 v42, v42
	v_exp_f32_e32 v43, v43
	s_waitcnt lgkmcnt(9)
	v_mfma_f32_32x32x16_bf16 v[0:15], v[32:35], v[220:223], v[0:15]
	ds_read_b64_tr_b16 v[220:221], v127 offset:20480
	ds_read_b64_tr_b16 v[222:223], v127 offset:20992
	v_add_f32_e32 v176, v40, v176
	v_add_f32_e32 v177, v41, v177
	v_cvt_pk_bf16_f32 v36, v40, v41
	v_add_f32_e32 v176, v42, v176
	v_mfma_f32_32x32x16_bf16 v[16:31], v[32:35], v[244:247], v[16:31]
	ds_read_b64_tr_b16 v[244:245], v127 offset:24576
	ds_read_b64_tr_b16 v[246:247], v127 offset:25088
	v_add_f32_e32 v177, v43, v177
	v_cvt_pk_bf16_f32 v37, v42, v43
	v_exp_f32_e32 v44, v44
	v_exp_f32_e32 v45, v45
	s_waitcnt lgkmcnt(12)
	v_mfma_f32_32x32x16_bf16 v[80:95], v[212:215], v[98:101], v[80:95]
	ds_read_b128 v[212:215], v194 offset:4096
	v_exp_f32_e32 v46, v46
	v_exp_f32_e32 v47, v47
	v_add_f32_e32 v176, v44, v176
	v_add_f32_e32 v177, v45, v177
	v_mfma_f32_32x32x16_bf16 v[64:79], v[216:219], v[98:101], v[64:79]
	ds_read_b128 v[216:219], v194 offset:4608
	v_cvt_pk_bf16_f32 v38, v44, v45
	v_add_f32_e32 v176, v46, v176
	v_add_f32_e32 v177, v47, v177
	v_cvt_pk_bf16_f32 v39, v46, v47
	s_waitcnt lgkmcnt(10)
	v_mfma_f32_32x32x16_bf16 v[0:15], v[36:39], v[240:243], v[0:15]
	v_add_f32_e32 v175, v176, v177
	v_mov_b32_e32 v178, v175
	v_add_f32_e32 v147, v147, v175
	s_nop 0
	v_mfma_f32_32x32x16_bf16 v[16:31], v[36:39], v[122:125], v[16:31]
	v_permlane32_swap_b32_e32 v175, v178
	v_add_f32_e32 v175, v175, v178
	v_cmp_lt_f32_e32 vcc, 0x43800000, v175
	s_cbranch_vccz .Lat_nr_10
	v_log_f32_e32 v175, v175
	s_nop 0
	v_max_f32_e32 v175, 0, v175
	v_exp_f32_e64 v178, -v175
	s_and_saveexec_b64 s[4:5], s[2:3]
	ds_write_b32 v143, v178 offset:40960
	s_or_b64 exec, exec, s[4:5]
	s_waitcnt lgkmcnt(0)
	v_add_u32_e32 v179, s33, v191
	v_sub_f32_e32 v224, v224, v175
	v_mul_f32_e32 v147, v147, v178
	ds_read_b128 v[48:51], v179 offset:40960
	ds_read_b128 v[52:55], v179 offset:40992
	ds_read_b128 v[56:59], v179 offset:41024
	ds_read_b128 v[60:63], v179 offset:41056
	s_waitcnt lgkmcnt(0)
	s_nop 15
	v_pk_mul_f32 v[0:1], v[0:1], v[48:49]
	v_pk_mul_f32 v[2:3], v[2:3], v[50:51]
	v_pk_mul_f32 v[4:5], v[4:5], v[52:53]
	v_pk_mul_f32 v[6:7], v[6:7], v[54:55]
	v_pk_mul_f32 v[8:9], v[8:9], v[56:57]
	v_pk_mul_f32 v[10:11], v[10:11], v[58:59]
	v_pk_mul_f32 v[12:13], v[12:13], v[60:61]
	v_pk_mul_f32 v[14:15], v[14:15], v[62:63]
	v_pk_mul_f32 v[16:17], v[16:17], v[48:49]
	v_pk_mul_f32 v[18:19], v[18:19], v[50:51]
	v_pk_mul_f32 v[20:21], v[20:21], v[52:53]
	v_pk_mul_f32 v[22:23], v[22:23], v[54:55]
	v_pk_mul_f32 v[24:25], v[24:25], v[56:57]
	v_pk_mul_f32 v[26:27], v[26:27], v[58:59]
	v_pk_mul_f32 v[28:29], v[28:29], v[60:61]
	v_pk_mul_f32 v[30:31], v[30:31], v[62:63]
	v_mov_b32_e32 v225, v224
	v_mov_b32_e32 v226, v224
	v_mov_b32_e32 v227, v224
	v_mov_b32_e32 v228, v224
	v_mov_b32_e32 v229, v224
	v_mov_b32_e32 v230, v224
	v_mov_b32_e32 v231, v224
	v_mov_b32_e32 v232, v224
	v_mov_b32_e32 v233, v224
	v_mov_b32_e32 v234, v224
	v_mov_b32_e32 v235, v224
	v_mov_b32_e32 v236, v224
	v_mov_b32_e32 v237, v224
	v_mov_b32_e32 v238, v224
	v_mov_b32_e32 v239, v224
	v_sub_f32_e32 v80, v80, v175
	v_sub_f32_e32 v81, v81, v175
	v_sub_f32_e32 v82, v82, v175
	v_sub_f32_e32 v83, v83, v175
	v_sub_f32_e32 v84, v84, v175
	v_sub_f32_e32 v85, v85, v175
	v_sub_f32_e32 v86, v86, v175
	v_sub_f32_e32 v87, v87, v175
	v_sub_f32_e32 v88, v88, v175
	v_sub_f32_e32 v89, v89, v175
	v_sub_f32_e32 v90, v90, v175
	v_sub_f32_e32 v91, v91, v175
	v_sub_f32_e32 v92, v92, v175
	v_sub_f32_e32 v93, v93, v175
	v_sub_f32_e32 v94, v94, v175
	v_sub_f32_e32 v95, v95, v175
	v_sub_f32_e32 v64, v64, v175
	v_sub_f32_e32 v65, v65, v175
	v_sub_f32_e32 v66, v66, v175
	v_sub_f32_e32 v67, v67, v175
	v_sub_f32_e32 v68, v68, v175
	v_sub_f32_e32 v69, v69, v175
	v_sub_f32_e32 v70, v70, v175
	v_sub_f32_e32 v71, v71, v175
	v_sub_f32_e32 v72, v72, v175
	v_sub_f32_e32 v73, v73, v175
	v_sub_f32_e32 v74, v74, v175
	v_sub_f32_e32 v75, v75, v175
	v_sub_f32_e32 v76, v76, v175
	v_sub_f32_e32 v77, v77, v175
	v_sub_f32_e32 v78, v78, v175
	v_sub_f32_e32 v79, v79, v175

; DEV void pvh(f32x16* o, int vb, bf16x8 pa, bf16x8 pb) {
;     s16x4 lo[4], hi[4];
; #pragma unroll
;     for (int d0 = 0; d0 < 2; ++d0)
; #pragma unroll
;         for (int kk = 0; kk < 2; ++kk) {
;             asm volatile("ds_read_b64_tr_b16 %0,%1 offset:%c2" : "=&v"(lo[d0 * 2 + kk]) : "v"(vb), "i"(d0 * 4096 + kk * 1024) : "memory");
;             asm volatile("ds_read_b64_tr_b16 %0,%1 offset:%c2" : "=&v"(hi[d0 * 2 + kk]) : "v"(vb), "i"(d0 * 4096 + kk * 1024 + 512) : "memory"); }
;     asm volatile("s_waitcnt lgkmcnt(0)" ::: "memory"); __builtin_amdgcn_sched_barrier(0);
;     ...
;     o[0] = __builtin_amdgcn_mfma_f32_32x32x16_bf16(pa, PKV(0), o[0], 0, 0, 0);
;     o[1] = __builtin_amdgcn_mfma_f32_32x32x16_bf16(pa, PKV(2), o[1], 0, 0, 0);
;     o[0] = __builtin_amdgcn_mfma_f32_32x32x16_bf16(pb, PKV(1), o[0], 0, 0, 0);
;     o[1] = __builtin_amdgcn_mfma_f32_32x32x16_bf16(pb, PKV(3), o[1], 0, 0, 0);
;     ...
; }
.Lat_k2_11:
	s_add_u32 s12, s12, 0x30000
	s_addc_u32 s13, s13, 0
	s_add_i32 m0, s22, 0x8000
	s_nop 0
	global_load_lds_dwordx4 v145, s[14:15]
	s_add_u32 s14, s14, 0x20000
	s_addc_u32 s15, s15, 0
	v_exp_f32_e32 v80, v80
	v_exp_f32_e32 v81, v81
	v_exp_f32_e32 v82, v82
	v_exp_f32_e32 v83, v83
	v_mov_b32_e32 v176, v80
	v_mov_b32_e32 v177, v81
	v_cvt_pk_bf16_f32 v80, v80, v81
	v_add_f32_e32 v176, v82, v176
	s_waitcnt lgkmcnt(8)
	v_mfma_f32_32x32x16_bf16 v[48:63], v[196:199], v[110:113], v[224:239]
	ds_read_b128 v[196:199], v194 offset:6144
	ds_read_b64_tr_b16 v[240:241], v127 offset:21504
	ds_read_b64_tr_b16 v[242:243], v127 offset:22016
	v_add_f32_e32 v177, v83, v177
	v_cvt_pk_bf16_f32 v81, v82, v83
	v_exp_f32_e32 v84, v84
	v_exp_f32_e32 v85, v85
	v_mfma_f32_32x32x16_bf16 v[32:47], v[200:203], v[110:113], v[224:239]
	ds_read_b128 v[200:203], v194 offset:6656
	ds_read_b64_tr_b16 v[122:123], v127 offset:25600
	ds_read_b64_tr_b16 v[124:125], v127 offset:26112
	v_exp_f32_e32 v86, v86
	v_exp_f32_e32 v87, v87
	v_add_f32_e32 v176, v84, v176
	v_add_f32_e32 v177, v85, v177
	s_waitcnt lgkmcnt(12)
	v_mfma_f32_32x32x16_bf16 v[48:63], v[204:207], v[106:109], v[48:63]
	ds_read_b128 v[204:207], v194 offset:8192
	v_cvt_pk_bf16_f32 v82, v84, v85
	v_add_f32_e32 v176, v86, v176
	v_add_f32_e32 v177, v87, v177
	v_cvt_pk_bf16_f32 v83, v86, v87
	v_mfma_f32_32x32x16_bf16 v[32:47], v[208:211], v[106:109], v[32:47]
	ds_read_b128 v[208:211], v194 offset:8704
	v_exp_f32_e32 v88, v88
	v_exp_f32_e32 v89, v89
	v_exp_f32_e32 v90, v90
	v_exp_f32_e32 v91, v91
	s_waitcnt lgkmcnt(8)
	v_mfma_f32_32x32x16_bf16 v[48:63], v[212:215], v[114:117], v[48:63]
	ds_read_b128 v[212:215], v194 offset:10240
	v_add_f32_e32 v176, v88, v176
	v_add_f32_e32 v177, v89, v177
	v_cvt_pk_bf16_f32 v84, v88, v89
	v_add_f32_e32 v176, v90, v176
	v_mfma_f32_32x32x16_bf16 v[0:15], v[80:83], v[220:223], v[0:15]
	ds_read_b64_tr_b16 v[220:221], v127 offset:22528
	ds_read_b64_tr_b16 v[222:223], v127 offset:23040
	v_add_f32_e32 v177, v91, v177
	v_cvt_pk_bf16_f32 v85, v90, v91
	v_exp_f32_e32 v92, v92
	v_exp_f32_e32 v93, v93
	v_mfma_f32_32x32x16_bf16 v[16:31], v[80:83], v[244:247], v[16:31]
	ds_read_b64_tr_b16 v[244:245], v127 offset:26624
	ds_read_b64_tr_b16 v[246:247], v127 offset:27136
	v_exp_f32_e32 v94, v94
	v_exp_f32_e32 v95, v95
	v_add_f32_e32 v176, v92, v176
	v_add_f32_e32 v177, v93, v177
	v_mfma_f32_32x32x16_bf16 v[32:47], v[216:219], v[114:117], v[32:47]
	ds_read_b128 v[216:219], v194 offset:10752
	v_cvt_pk_bf16_f32 v86, v92, v93
	v_add_f32_e32 v176, v94, v176
	v_add_f32_e32 v177, v95, v177
	v_cvt_pk_bf16_f32 v87, v94, v95
	s_waitcnt lgkmcnt(10)
	v_mfma_f32_32x32x16_bf16 v[48:63], v[196:199], v[118:121], v[48:63]
	v_exp_f32_e32 v64, v64
	v_exp_f32_e32 v65, v65
	v_exp_f32_e32 v66, v66
	v_exp_f32_e32 v67, v67
	v_mfma_f32_32x32x16_bf16 v[32:47], v[200:203], v[118:121], v[32:47]
	v_add_f32_e32 v176, v64, v176
	v_add_f32_e32 v177, v65, v177
	v_cvt_pk_bf16_f32 v64, v64, v65
	v_add_f32_e32 v176, v66, v176
	s_waitcnt lgkmcnt(8)
	v_mfma_f32_32x32x16_bf16 v[0:15], v[84:87], v[240:243], v[0:15]
	ds_read_b64_tr_b16 v[240:241], v127 offset:23552
	ds_read_b64_tr_b16 v[242:243], v127 offset:24064
	v_add_f32_e32 v177, v67, v177
	v_cvt_pk_bf16_f32 v65, v66, v67
	v_exp_f32_e32 v68, v68
	v_exp_f32_e32 v69, v69
	v_mfma_f32_32x32x16_bf16 v[16:31], v[84:87], v[122:125], v[16:31]
	ds_read_b64_tr_b16 v[122:123], v127 offset:27648
	ds_read_b64_tr_b16 v[124:125], v127 offset:28160
	v_exp_f32_e32 v70, v70
	v_exp_f32_e32 v71, v71
	v_add_f32_e32 v176, v68, v176
	v_add_f32_e32 v177, v69, v177
	s_waitcnt vmcnt(2)
	s_barrier
; DEV void pvh(f32x16* o, int vb, bf16x8 pa, bf16x8 pb) {
;     s16x4 lo[4], hi[4];
; #pragma unroll
;     for (int d0 = 0; d0 < 2; ++d0)
; #pragma unroll
;         for (int kk = 0; kk < 2; ++kk) {
;             asm volatile("ds_read_b64_tr_b16 %0,%1 offset:%c2" : "=&v"(lo[d0 * 2 + kk]) : "v"(vb), "i"(d0 * 4096 + kk * 1024) : "memory");
;             asm volatile("ds_read_b64_tr_b16 %0,%1 offset:%c2" : "=&v"(hi[d0 * 2 + kk]) : "v"(vb), "i"(d0 * 4096 + kk * 1024 + 512) : "memory"); }
;     asm volatile("s_waitcnt lgkmcnt(0)" ::: "memory"); __builtin_amdgcn_sched_barrier(0);
;     ...
;     o[0] = __builtin_amdgcn_mfma_f32_32x32x16_bf16(pa, PKV(0), o[0], 0, 0, 0);
;     o[1] = __builtin_amdgcn_mfma_f32_32x32x16_bf16(pa, PKV(2), o[1], 0, 0, 0);
;     o[0] = __builtin_amdgcn_mfma_f32_32x32x16_bf16(pb, PKV(1), o[0], 0, 0, 0);
;     o[1] = __builtin_amdgcn_mfma_f32_32x32x16_bf16(pb, PKV(3), o[1], 0, 0, 0);
;     ...
; }
	s_waitcnt lgkmcnt(10)
	v_mfma_f32_32x32x16_bf16 v[48:63], v[204:207], v[102:105], v[48:63]
	ds_read_b128 v[196:199], v194 offset:20480
	ds_read_b128 v[200:203], v194 offset:20992
	ds_read_b128 v[204:207], v194 offset:22528
	v_cvt_pk_bf16_f32 v66, v68, v69
	v_add_f32_e32 v176, v70, v176
	v_add_f32_e32 v177, v71, v177
	v_cvt_pk_bf16_f32 v67, v70, v71
	v_mfma_f32_32x32x16_bf16 v[32:47], v[208:211], v[102:105], v[32:47]
	ds_read_b128 v[208:211], v194 offset:23040
	v_exp_f32_e32 v72, v72
	v_exp_f32_e32 v73, v73
	v_exp_f32_e32 v74, v74
	v_exp_f32_e32 v75, v75
	s_waitcnt lgkmcnt(9)
	v_mfma_f32_32x32x16_bf16 v[0:15], v[64:67], v[220:223], v[0:15]
	ds_read_b64_tr_b16 v[220:221], v139 offset:0
	ds_read_b64_tr_b16 v[222:223], v139 offset:512
	v_add_f32_e32 v176, v72, v176
	v_add_f32_e32 v177, v73, v177
	v_cvt_pk_bf16_f32 v68, v72, v73
	v_add_f32_e32 v176, v74, v176
	v_mfma_f32_32x32x16_bf16 v[16:31], v[64:67], v[244:247], v[16:31]
	ds_read_b64_tr_b16 v[244:245], v139 offset:4096
	ds_read_b64_tr_b16 v[246:247], v139 offset:4608
	v_add_f32_e32 v177, v75, v177
	v_cvt_pk_bf16_f32 v69, v74, v75
	v_exp_f32_e32 v76, v76
	v_exp_f32_e32 v77, v77
	s_waitcnt lgkmcnt(12)
	v_mfma_f32_32x32x16_bf16 v[48:63], v[212:215], v[98:101], v[48:63]
	ds_read_b128 v[212:215], v194 offset:24576
	v_exp_f32_e32 v78, v78
	v_exp_f32_e32 v79, v79
	v_add_f32_e32 v176, v76, v176
	v_add_f32_e32 v177, v77, v177
	v_mfma_f32_32x32x16_bf16 v[32:47], v[216:219], v[98:101], v[32:47]
	ds_read_b128 v[216:219], v194 offset:25088
	v_cvt_pk_bf16_f32 v70, v76, v77
	v_add_f32_e32 v176, v78, v176
	v_add_f32_e32 v177, v79, v177
	v_cvt_pk_bf16_f32 v71, v78, v79
	s_waitcnt lgkmcnt(10)
	v_mfma_f32_32x32x16_bf16 v[0:15], v[68:71], v[240:243], v[0:15]
	v_add_f32_e32 v175, v176, v177
	v_mov_b32_e32 v178, v175
	v_add_f32_e32 v147, v147, v175
	s_nop 0
	v_mfma_f32_32x32x16_bf16 v[16:31], v[68:71], v[122:125], v[16:31]
	v_permlane32_swap_b32_e32 v175, v178
	v_add_f32_e32 v175, v175, v178
	v_cmp_lt_f32_e32 vcc, 0x43800000, v175
	s_cbranch_vccz .Lat_nr_12
	v_log_f32_e32 v175, v175
	s_nop 0
	v_max_f32_e32 v175, 0, v175
	v_exp_f32_e64 v178, -v175
	s_and_saveexec_b64 s[4:5], s[2:3]
	ds_write_b32 v143, v178 offset:40960
	s_or_b64 exec, exec, s[4:5]
	s_waitcnt lgkmcnt(0)
	v_add_u32_e32 v179, s33, v191
	v_sub_f32_e32 v224, v224, v175
	v_mul_f32_e32 v147, v147, v178
	ds_read_b128 v[80:83], v179 offset:40960
	ds_read_b128 v[84:87], v179 offset:40992
	ds_read_b128 v[88:91], v179 offset:41024
	ds_read_b128 v[92:95], v179 offset:41056
	s_waitcnt lgkmcnt(0)
	s_nop 15
	v_pk_mul_f32 v[0:1], v[0:1], v[80:81]
	v_pk_mul_f32 v[2:3], v[2:3], v[82:83]
	v_pk_mul_f32 v[4:5], v[4:5], v[84:85]
	v_pk_mul_f32 v[6:7], v[6:7], v[86:87]
	v_pk_mul_f32 v[8:9], v[8:9], v[88:89]
	v_pk_mul_f32 v[10:11], v[10:11], v[90:91]
	v_pk_mul_f32 v[12:13], v[12:13], v[92:93]
	v_pk_mul_f32 v[14:15], v[14:15], v[94:95]
	v_pk_mul_f32 v[16:17], v[16:17], v[80:81]
	v_pk_mul_f32 v[18:19], v[18:19], v[82:83]
	v_pk_mul_f32 v[20:21], v[20:21], v[84:85]
	v_pk_mul_f32 v[22:23], v[22:23], v[86:87]
	v_pk_mul_f32 v[24:25], v[24:25], v[88:89]
	v_pk_mul_f32 v[26:27], v[26:27], v[90:91]
	v_pk_mul_f32 v[28:29], v[28:29], v[92:93]
	v_pk_mul_f32 v[30:31], v[30:31], v[94:95]
	v_mov_b32_e32 v225, v224
	v_mov_b32_e32 v226, v224
	v_mov_b32_e32 v227, v224
	v_mov_b32_e32 v228, v224
	v_mov_b32_e32 v229, v224
	v_mov_b32_e32 v230, v224
	v_mov_b32_e32 v231, v224
	v_mov_b32_e32 v232, v224
	v_mov_b32_e32 v233, v224
	v_mov_b32_e32 v234, v224
	v_mov_b32_e32 v235, v224
	v_mov_b32_e32 v236, v224
	v_mov_b32_e32 v237, v224
	v_mov_b32_e32 v238, v224
	v_mov_b32_e32 v239, v224
	v_sub_f32_e32 v48, v48, v175
	v_sub_f32_e32 v49, v49, v175
	v_sub_f32_e32 v50, v50, v175
	v_sub_f32_e32 v51, v51, v175
	v_sub_f32_e32 v52, v52, v175
	v_sub_f32_e32 v53, v53, v175
	v_sub_f32_e32 v54, v54, v175
	v_sub_f32_e32 v55, v55, v175
	v_sub_f32_e32 v56, v56, v175
	v_sub_f32_e32 v57, v57, v175
	v_sub_f32_e32 v58, v58, v175
	v_sub_f32_e32 v59, v59, v175
	v_sub_f32_e32 v60, v60, v175
	v_sub_f32_e32 v61, v61, v175
	v_sub_f32_e32 v62, v62, v175
	v_sub_f32_e32 v63, v63, v175
	v_sub_f32_e32 v32, v32, v175
	v_sub_f32_e32 v33, v33, v175
	v_sub_f32_e32 v34, v34, v175
	v_sub_f32_e32 v35, v35, v175
	v_sub_f32_e32 v36, v36, v175
	v_sub_f32_e32 v37, v37, v175
	v_sub_f32_e32 v38, v38, v175
	v_sub_f32_e32 v39, v39, v175
	v_sub_f32_e32 v40, v40, v175
	v_sub_f32_e32 v41, v41, v175
	v_sub_f32_e32 v42, v42, v175
	v_sub_f32_e32 v43, v43, v175
	v_sub_f32_e32 v44, v44, v175
	v_sub_f32_e32 v45, v45, v175
	v_sub_f32_e32 v46, v46, v175
	v_sub_f32_e32 v47, v47, v175

; DEV void pvh(f32x16* o, int vb, bf16x8 pa, bf16x8 pb) {
;     s16x4 lo[4], hi[4];
; #pragma unroll
;     for (int d0 = 0; d0 < 2; ++d0)
; #pragma unroll
;         for (int kk = 0; kk < 2; ++kk) {
;             asm volatile("ds_read_b64_tr_b16 %0,%1 offset:%c2" : "=&v"(lo[d0 * 2 + kk]) : "v"(vb), "i"(d0 * 4096 + kk * 1024) : "memory");
;             asm volatile("ds_read_b64_tr_b16 %0,%1 offset:%c2" : "=&v"(hi[d0 * 2 + kk]) : "v"(vb), "i"(d0 * 4096 + kk * 1024 + 512) : "memory"); }
;     asm volatile("s_waitcnt lgkmcnt(0)" ::: "memory"); __builtin_amdgcn_sched_barrier(0);
;     ...
;     o[0] = __builtin_amdgcn_mfma_f32_32x32x16_bf16(pa, PKV(0), o[0], 0, 0, 0);
;     o[1] = __builtin_amdgcn_mfma_f32_32x32x16_bf16(pa, PKV(2), o[1], 0, 0, 0);
;     o[0] = __builtin_amdgcn_mfma_f32_32x32x16_bf16(pb, PKV(1), o[0], 0, 0, 0);
;     o[1] = __builtin_amdgcn_mfma_f32_32x32x16_bf16(pb, PKV(3), o[1], 0, 0, 0);
;     ...
; }
.Lat_k2_13:
	s_add_i32 m0, s22, 0x13000
	s_nop 0
	global_load_lds_dwordx4 v145, s[14:15]
	s_add_u32 s14, s14, 0x20000
	s_addc_u32 s15, s15, 0
	v_exp_f32_e32 v48, v48
	v_exp_f32_e32 v49, v49
	v_exp_f32_e32 v50, v50
	v_exp_f32_e32 v51, v51
	v_mov_b32_e32 v176, v48
	v_mov_b32_e32 v177, v49
	v_cvt_pk_bf16_f32 v48, v48, v49
	v_add_f32_e32 v176, v50, v176
	s_waitcnt lgkmcnt(8)
	v_mfma_f32_32x32x16_bf16 v[80:95], v[196:199], v[110:113], v[224:239]
	ds_read_b128 v[196:199], v194 offset:26624
	ds_read_b64_tr_b16 v[240:241], v139 offset:1024
	ds_read_b64_tr_b16 v[242:243], v139 offset:1536
	v_add_f32_e32 v177, v51, v177
	v_cvt_pk_bf16_f32 v49, v50, v51
	v_exp_f32_e32 v52, v52
	v_exp_f32_e32 v53, v53
	v_mfma_f32_32x32x16_bf16 v[64:79], v[200:203], v[110:113], v[224:239]
	ds_read_b128 v[200:203], v194 offset:27136
	ds_read_b64_tr_b16 v[122:123], v139 offset:5120
	ds_read_b64_tr_b16 v[124:125], v139 offset:5632
	v_exp_f32_e32 v54, v54
	v_exp_f32_e32 v55, v55
	v_add_f32_e32 v176, v52, v176
	v_add_f32_e32 v177, v53, v177
	s_waitcnt lgkmcnt(12)
	v_mfma_f32_32x32x16_bf16 v[80:95], v[204:207], v[106:109], v[80:95]
	ds_read_b128 v[204:207], v194 offset:28672
	v_cvt_pk_bf16_f32 v50, v52, v53
	v_add_f32_e32 v176, v54, v176
	v_add_f32_e32 v177, v55, v177
	v_cvt_pk_bf16_f32 v51, v54, v55
	v_mfma_f32_32x32x16_bf16 v[64:79], v[208:211], v[106:109], v[64:79]
	ds_read_b128 v[208:211], v194 offset:29184
	v_exp_f32_e32 v56, v56
	v_exp_f32_e32 v57, v57
	v_exp_f32_e32 v58, v58
	v_exp_f32_e32 v59, v59
	s_waitcnt lgkmcnt(8)
	v_mfma_f32_32x32x16_bf16 v[80:95], v[212:215], v[114:117], v[80:95]
	ds_read_b128 v[212:215], v194 offset:30720
	v_add_f32_e32 v176, v56, v176
	v_add_f32_e32 v177, v57, v177
	v_cvt_pk_bf16_f32 v52, v56, v57
	v_add_f32_e32 v176, v58, v176
	v_mfma_f32_32x32x16_bf16 v[0:15], v[48:51], v[220:223], v[0:15]
	ds_read_b64_tr_b16 v[220:221], v139 offset:2048
	ds_read_b64_tr_b16 v[222:223], v139 offset:2560
	v_add_f32_e32 v177, v59, v177
	v_cvt_pk_bf16_f32 v53, v58, v59
	v_exp_f32_e32 v60, v60
	v_exp_f32_e32 v61, v61
	v_mfma_f32_32x32x16_bf16 v[16:31], v[48:51], v[244:247], v[16:31]
	ds_read_b64_tr_b16 v[244:245], v139 offset:6144
	ds_read_b64_tr_b16 v[246:247], v139 offset:6656
	v_exp_f32_e32 v62, v62
	v_exp_f32_e32 v63, v63
	v_add_f32_e32 v176, v60, v176
	v_add_f32_e32 v177, v61, v177
	v_mfma_f32_32x32x16_bf16 v[64:79], v[216:219], v[114:117], v[64:79]
	ds_read_b128 v[216:219], v194 offset:31232
	v_cvt_pk_bf16_f32 v54, v60, v61
	v_add_f32_e32 v176, v62, v176
	v_add_f32_e32 v177, v63, v177
	v_cvt_pk_bf16_f32 v55, v62, v63
	s_waitcnt lgkmcnt(10)
	v_mfma_f32_32x32x16_bf16 v[80:95], v[196:199], v[118:121], v[80:95]
	v_exp_f32_e32 v32, v32
	v_exp_f32_e32 v33, v33
	v_exp_f32_e32 v34, v34
	v_exp_f32_e32 v35, v35
	v_mfma_f32_32x32x16_bf16 v[64:79], v[200:203], v[118:121], v[64:79]
	v_add_f32_e32 v176, v32, v176
	v_add_f32_e32 v177, v33, v177
	v_cvt_pk_bf16_f32 v32, v32, v33
	v_add_f32_e32 v176, v34, v176
	s_waitcnt lgkmcnt(8)
	v_mfma_f32_32x32x16_bf16 v[0:15], v[52:55], v[240:243], v[0:15]
	ds_read_b64_tr_b16 v[240:241], v139 offset:3072
	ds_read_b64_tr_b16 v[242:243], v139 offset:3584
	v_add_f32_e32 v177, v35, v177
	v_cvt_pk_bf16_f32 v33, v34, v35
	v_exp_f32_e32 v36, v36
	v_exp_f32_e32 v37, v37
	v_mfma_f32_32x32x16_bf16 v[16:31], v[52:55], v[122:125], v[16:31]
	ds_read_b64_tr_b16 v[122:123], v139 offset:7168
	ds_read_b64_tr_b16 v[124:125], v139 offset:7680
	v_exp_f32_e32 v38, v38
	v_exp_f32_e32 v39, v39
	v_add_f32_e32 v176, v36, v176
	v_add_f32_e32 v177, v37, v177
	s_waitcnt vmcnt(2)
	s_barrier
; DEV void pvh(f32x16* o, int vb, bf16x8 pa, bf16x8 pb) {
;     s16x4 lo[4], hi[4];
; #pragma unroll
;     for (int d0 = 0; d0 < 2; ++d0)
; #pragma unroll
;         for (int kk = 0; kk < 2; ++kk) {
;             asm volatile("ds_read_b64_tr_b16 %0,%1 offset:%c2" : "=&v"(lo[d0 * 2 + kk]) : "v"(vb), "i"(d0 * 4096 + kk * 1024) : "memory");
;             asm volatile("ds_read_b64_tr_b16 %0,%1 offset:%c2" : "=&v"(hi[d0 * 2 + kk]) : "v"(vb), "i"(d0 * 4096 + kk * 1024 + 512) : "memory"); }
;     asm volatile("s_waitcnt lgkmcnt(0)" ::: "memory"); __builtin_amdgcn_sched_barrier(0);
;     ...
;     o[0] = __builtin_amdgcn_mfma_f32_32x32x16_bf16(pa, PKV(0), o[0], 0, 0, 0);
;     o[1] = __builtin_amdgcn_mfma_f32_32x32x16_bf16(pa, PKV(2), o[1], 0, 0, 0);
;     o[0] = __builtin_amdgcn_mfma_f32_32x32x16_bf16(pb, PKV(1), o[0], 0, 0, 0);
;     o[1] = __builtin_amdgcn_mfma_f32_32x32x16_bf16(pb, PKV(3), o[1], 0, 0, 0);
;     ...
; }
	s_waitcnt lgkmcnt(10)
	v_mfma_f32_32x32x16_bf16 v[80:95], v[204:207], v[102:105], v[80:95]
	ds_read_b128 v[196:199], v126 offset:0
	ds_read_b128 v[200:203], v126 offset:512
	ds_read_b128 v[204:207], v126 offset:2048
	v_cvt_pk_bf16_f32 v34, v36, v37
	v_add_f32_e32 v176, v38, v176
	v_add_f32_e32 v177, v39, v177
	v_cvt_pk_bf16_f32 v35, v38, v39
	v_mfma_f32_32x32x16_bf16 v[64:79], v[208:211], v[102:105], v[64:79]
	ds_read_b128 v[208:211], v126 offset:2560
	v_exp_f32_e32 v40, v40
	v_exp_f32_e32 v41, v41
	v_exp_f32_e32 v42, v42
	v_exp_f32_e32 v43, v43
	s_waitcnt lgkmcnt(9)
	v_mfma_f32_32x32x16_bf16 v[0:15], v[32:35], v[220:223], v[0:15]
	ds_read_b64_tr_b16 v[220:221], v139 offset:20480
	ds_read_b64_tr_b16 v[222:223], v139 offset:20992
	v_add_f32_e32 v176, v40, v176
	v_add_f32_e32 v177, v41, v177
	v_cvt_pk_bf16_f32 v36, v40, v41
	v_add_f32_e32 v176, v42, v176
	v_mfma_f32_32x32x16_bf16 v[16:31], v[32:35], v[244:247], v[16:31]
	ds_read_b64_tr_b16 v[244:245], v139 offset:24576
	ds_read_b64_tr_b16 v[246:247], v139 offset:25088
	v_add_f32_e32 v177, v43, v177
	v_cvt_pk_bf16_f32 v37, v42, v43
	v_exp_f32_e32 v44, v44
	v_exp_f32_e32 v45, v45
	s_waitcnt lgkmcnt(12)
	v_mfma_f32_32x32x16_bf16 v[80:95], v[212:215], v[98:101], v[80:95]
	ds_read_b128 v[212:215], v126 offset:4096
	v_exp_f32_e32 v46, v46
	v_exp_f32_e32 v47, v47
	v_add_f32_e32 v176, v44, v176
	v_add_f32_e32 v177, v45, v177
	v_mfma_f32_32x32x16_bf16 v[64:79], v[216:219], v[98:101], v[64:79]
	ds_read_b128 v[216:219], v126 offset:4608
	v_cvt_pk_bf16_f32 v38, v44, v45
	v_add_f32_e32 v176, v46, v176
	v_add_f32_e32 v177, v47, v177
	v_cvt_pk_bf16_f32 v39, v46, v47
	s_waitcnt lgkmcnt(10)
	v_mfma_f32_32x32x16_bf16 v[0:15], v[36:39], v[240:243], v[0:15]
	v_add_f32_e32 v175, v176, v177
	v_mov_b32_e32 v178, v175
	v_add_f32_e32 v147, v147, v175
	s_nop 0
	v_mfma_f32_32x32x16_bf16 v[16:31], v[36:39], v[122:125], v[16:31]
	v_permlane32_swap_b32_e32 v175, v178
	v_add_f32_e32 v175, v175, v178
	v_cmp_lt_f32_e32 vcc, 0x43800000, v175
	s_cbranch_vccz .Lat_nr_14
	v_log_f32_e32 v175, v175
	s_nop 0
	v_max_f32_e32 v175, 0, v175
	v_exp_f32_e64 v178, -v175
	s_and_saveexec_b64 s[4:5], s[2:3]
	ds_write_b32 v143, v178 offset:40960
	s_or_b64 exec, exec, s[4:5]
	s_waitcnt lgkmcnt(0)
	v_add_u32_e32 v179, s33, v191
	v_sub_f32_e32 v224, v224, v175
	v_mul_f32_e32 v147, v147, v178
	ds_read_b128 v[48:51], v179 offset:40960
	ds_read_b128 v[52:55], v179 offset:40992
	ds_read_b128 v[56:59], v179 offset:41024
	ds_read_b128 v[60:63], v179 offset:41056
	s_waitcnt lgkmcnt(0)
	s_nop 15
	v_pk_mul_f32 v[0:1], v[0:1], v[48:49]
	v_pk_mul_f32 v[2:3], v[2:3], v[50:51]
	v_pk_mul_f32 v[4:5], v[4:5], v[52:53]
	v_pk_mul_f32 v[6:7], v[6:7], v[54:55]
	v_pk_mul_f32 v[8:9], v[8:9], v[56:57]
	v_pk_mul_f32 v[10:11], v[10:11], v[58:59]
	v_pk_mul_f32 v[12:13], v[12:13], v[60:61]
	v_pk_mul_f32 v[14:15], v[14:15], v[62:63]
	v_pk_mul_f32 v[16:17], v[16:17], v[48:49]
	v_pk_mul_f32 v[18:19], v[18:19], v[50:51]
	v_pk_mul_f32 v[20:21], v[20:21], v[52:53]
	v_pk_mul_f32 v[22:23], v[22:23], v[54:55]
	v_pk_mul_f32 v[24:25], v[24:25], v[56:57]
	v_pk_mul_f32 v[26:27], v[26:27], v[58:59]
	v_pk_mul_f32 v[28:29], v[28:29], v[60:61]
	v_pk_mul_f32 v[30:31], v[30:31], v[62:63]
	v_mov_b32_e32 v225, v224
	v_mov_b32_e32 v226, v224
	v_mov_b32_e32 v227, v224
	v_mov_b32_e32 v228, v224
	v_mov_b32_e32 v229, v224
	v_mov_b32_e32 v230, v224
	v_mov_b32_e32 v231, v224
	v_mov_b32_e32 v232, v224
	v_mov_b32_e32 v233, v224
	v_mov_b32_e32 v234, v224
	v_mov_b32_e32 v235, v224
	v_mov_b32_e32 v236, v224
	v_mov_b32_e32 v237, v224
	v_mov_b32_e32 v238, v224
	v_mov_b32_e32 v239, v224
	v_sub_f32_e32 v80, v80, v175
	v_sub_f32_e32 v81, v81, v175
	v_sub_f32_e32 v82, v82, v175
	v_sub_f32_e32 v83, v83, v175
	v_sub_f32_e32 v84, v84, v175
	v_sub_f32_e32 v85, v85, v175
	v_sub_f32_e32 v86, v86, v175
	v_sub_f32_e32 v87, v87, v175
	v_sub_f32_e32 v88, v88, v175
	v_sub_f32_e32 v89, v89, v175
	v_sub_f32_e32 v90, v90, v175
	v_sub_f32_e32 v91, v91, v175
	v_sub_f32_e32 v92, v92, v175
	v_sub_f32_e32 v93, v93, v175
	v_sub_f32_e32 v94, v94, v175
	v_sub_f32_e32 v95, v95, v175
	v_sub_f32_e32 v64, v64, v175
	v_sub_f32_e32 v65, v65, v175
	v_sub_f32_e32 v66, v66, v175
	v_sub_f32_e32 v67, v67, v175
	v_sub_f32_e32 v68, v68, v175
	v_sub_f32_e32 v69, v69, v175
	v_sub_f32_e32 v70, v70, v175
	v_sub_f32_e32 v71, v71, v175
	v_sub_f32_e32 v72, v72, v175
	v_sub_f32_e32 v73, v73, v175
	v_sub_f32_e32 v74, v74, v175
	v_sub_f32_e32 v75, v75, v175
	v_sub_f32_e32 v76, v76, v175
	v_sub_f32_e32 v77, v77, v175
	v_sub_f32_e32 v78, v78, v175
	v_sub_f32_e32 v79, v79, v175

; DEV void pvh(f32x16* o, int vb, bf16x8 pa, bf16x8 pb) {
;     s16x4 lo[4], hi[4];
; #pragma unroll
;     for (int d0 = 0; d0 < 2; ++d0)
; #pragma unroll
;         for (int kk = 0; kk < 2; ++kk) {
;             asm volatile("ds_read_b64_tr_b16 %0,%1 offset:%c2" : "=&v"(lo[d0 * 2 + kk]) : "v"(vb), "i"(d0 * 4096 + kk * 1024) : "memory");
;             asm volatile("ds_read_b64_tr_b16 %0,%1 offset:%c2" : "=&v"(hi[d0 * 2 + kk]) : "v"(vb), "i"(d0 * 4096 + kk * 1024 + 512) : "memory"); }
;     asm volatile("s_waitcnt lgkmcnt(0)" ::: "memory"); __builtin_amdgcn_sched_barrier(0);
;     ...
;     o[0] = __builtin_amdgcn_mfma_f32_32x32x16_bf16(pa, PKV(0), o[0], 0, 0, 0);
;     o[1] = __builtin_amdgcn_mfma_f32_32x32x16_bf16(pa, PKV(2), o[1], 0, 0, 0);
;     o[0] = __builtin_amdgcn_mfma_f32_32x32x16_bf16(pb, PKV(1), o[0], 0, 0, 0);
;     o[1] = __builtin_amdgcn_mfma_f32_32x32x16_bf16(pb, PKV(3), o[1], 0, 0, 0);
;     ...
; }
.Lat_k2_15:
	s_add_u32 s12, s12, 0x30000
	s_addc_u32 s13, s13, 0
	s_add_i32 m0, s22, 0x18000
	s_nop 0
	global_load_lds_dwordx4 v145, s[14:15]
	v_exp_f32_e32 v80, v80
	v_exp_f32_e32 v81, v81
	v_exp_f32_e32 v82, v82
	v_exp_f32_e32 v83, v83
	v_mov_b32_e32 v176, v80
	v_mov_b32_e32 v177, v81
	v_cvt_pk_bf16_f32 v80, v80, v81
	v_add_f32_e32 v176, v82, v176
	s_waitcnt lgkmcnt(8)
	v_mfma_f32_32x32x16_bf16 v[48:63], v[196:199], v[110:113], v[224:239]
	ds_read_b128 v[196:199], v126 offset:6144
	ds_read_b64_tr_b16 v[240:241], v139 offset:21504
	ds_read_b64_tr_b16 v[242:243], v139 offset:22016
	v_add_f32_e32 v177, v83, v177
	v_cvt_pk_bf16_f32 v81, v82, v83
	v_exp_f32_e32 v84, v84
	v_exp_f32_e32 v85, v85
	v_mfma_f32_32x32x16_bf16 v[32:47], v[200:203], v[110:113], v[224:239]
	ds_read_b128 v[200:203], v126 offset:6656
	ds_read_b64_tr_b16 v[122:123], v139 offset:25600
	ds_read_b64_tr_b16 v[124:125], v139 offset:26112
	v_exp_f32_e32 v86, v86
	v_exp_f32_e32 v87, v87
	v_add_f32_e32 v176, v84, v176
	v_add_f32_e32 v177, v85, v177
	s_waitcnt lgkmcnt(12)
	v_mfma_f32_32x32x16_bf16 v[48:63], v[204:207], v[106:109], v[48:63]
	ds_read_b128 v[204:207], v126 offset:8192
	v_cvt_pk_bf16_f32 v82, v84, v85
	v_add_f32_e32 v176, v86, v176
	v_add_f32_e32 v177, v87, v177
	v_cvt_pk_bf16_f32 v83, v86, v87
	v_mfma_f32_32x32x16_bf16 v[32:47], v[208:211], v[106:109], v[32:47]
	ds_read_b128 v[208:211], v126 offset:8704
	v_exp_f32_e32 v88, v88
	v_exp_f32_e32 v89, v89
	v_exp_f32_e32 v90, v90
	v_exp_f32_e32 v91, v91
	s_waitcnt lgkmcnt(8)
	v_mfma_f32_32x32x16_bf16 v[48:63], v[212:215], v[114:117], v[48:63]
	ds_read_b128 v[212:215], v126 offset:10240
	v_add_f32_e32 v176, v88, v176
	v_add_f32_e32 v177, v89, v177
	v_cvt_pk_bf16_f32 v84, v88, v89
	v_add_f32_e32 v176, v90, v176
	v_mfma_f32_32x32x16_bf16 v[0:15], v[80:83], v[220:223], v[0:15]
	ds_read_b64_tr_b16 v[220:221], v139 offset:22528
	ds_read_b64_tr_b16 v[222:223], v139 offset:23040
	v_add_f32_e32 v177, v91, v177
	v_cvt_pk_bf16_f32 v85, v90, v91
	v_exp_f32_e32 v92, v92
	v_exp_f32_e32 v93, v93
	v_mfma_f32_32x32x16_bf16 v[16:31], v[80:83], v[244:247], v[16:31]
	ds_read_b64_tr_b16 v[244:245], v139 offset:26624
	ds_read_b64_tr_b16 v[246:247], v139 offset:27136
	v_exp_f32_e32 v94, v94
	v_exp_f32_e32 v95, v95
	v_add_f32_e32 v176, v92, v176
	v_add_f32_e32 v177, v93, v177
	v_mfma_f32_32x32x16_bf16 v[32:47], v[216:219], v[114:117], v[32:47]
	ds_read_b128 v[216:219], v126 offset:10752
	v_cvt_pk_bf16_f32 v86, v92, v93
	v_add_f32_e32 v176, v94, v176
	v_add_f32_e32 v177, v95, v177
	v_cvt_pk_bf16_f32 v87, v94, v95
	s_waitcnt lgkmcnt(10)
	v_mfma_f32_32x32x16_bf16 v[48:63], v[196:199], v[118:121], v[48:63]
	v_exp_f32_e32 v64, v64
	v_exp_f32_e32 v65, v65
	v_exp_f32_e32 v66, v66
	v_exp_f32_e32 v67, v67
	v_mfma_f32_32x32x16_bf16 v[32:47], v[200:203], v[118:121], v[32:47]
	v_add_f32_e32 v176, v64, v176
	v_add_f32_e32 v177, v65, v177
	v_cvt_pk_bf16_f32 v64, v64, v65
	v_add_f32_e32 v176, v66, v176
	s_waitcnt lgkmcnt(8)
	v_mfma_f32_32x32x16_bf16 v[0:15], v[84:87], v[240:243], v[0:15]
	ds_read_b64_tr_b16 v[240:241], v139 offset:23552
	ds_read_b64_tr_b16 v[242:243], v139 offset:24064
	v_add_f32_e32 v177, v67, v177
	v_cvt_pk_bf16_f32 v65, v66, v67
	v_exp_f32_e32 v68, v68
	v_exp_f32_e32 v69, v69
	v_mfma_f32_32x32x16_bf16 v[16:31], v[84:87], v[122:125], v[16:31]
	ds_read_b64_tr_b16 v[122:123], v139 offset:27648
	ds_read_b64_tr_b16 v[124:125], v139 offset:28160
	v_exp_f32_e32 v70, v70
	v_exp_f32_e32 v71, v71
	v_add_f32_e32 v176, v68, v176
	v_add_f32_e32 v177, v69, v177
	s_waitcnt vmcnt(2)
	s_barrier
; DEV void pvh(f32x16* o, int vb, bf16x8 pa, bf16x8 pb) {
;     s16x4 lo[4], hi[4];
; #pragma unroll
;     for (int d0 = 0; d0 < 2; ++d0)
; #pragma unroll
;         for (int kk = 0; kk < 2; ++kk) {
;             asm volatile("ds_read_b64_tr_b16 %0,%1 offset:%c2" : "=&v"(lo[d0 * 2 + kk]) : "v"(vb), "i"(d0 * 4096 + kk * 1024) : "memory");
;             asm volatile("ds_read_b64_tr_b16 %0,%1 offset:%c2" : "=&v"(hi[d0 * 2 + kk]) : "v"(vb), "i"(d0 * 4096 + kk * 1024 + 512) : "memory"); }
;     asm volatile("s_waitcnt lgkmcnt(0)" ::: "memory"); __builtin_amdgcn_sched_barrier(0);
;     ...
;     o[0] = __builtin_amdgcn_mfma_f32_32x32x16_bf16(pa, PKV(0), o[0], 0, 0, 0);
;     o[1] = __builtin_amdgcn_mfma_f32_32x32x16_bf16(pa, PKV(2), o[1], 0, 0, 0);
;     o[0] = __builtin_amdgcn_mfma_f32_32x32x16_bf16(pb, PKV(1), o[0], 0, 0, 0);
;     o[1] = __builtin_amdgcn_mfma_f32_32x32x16_bf16(pb, PKV(3), o[1], 0, 0, 0);
;     ...
; }
	s_waitcnt lgkmcnt(10)
	v_mfma_f32_32x32x16_bf16 v[48:63], v[204:207], v[102:105], v[48:63]
	ds_read_b128 v[196:199], v126 offset:20480
	ds_read_b128 v[200:203], v126 offset:20992
	ds_read_b128 v[204:207], v126 offset:22528
	v_cvt_pk_bf16_f32 v66, v68, v69
	v_add_f32_e32 v176, v70, v176
	v_add_f32_e32 v177, v71, v177
	v_cvt_pk_bf16_f32 v67, v70, v71
	v_mfma_f32_32x32x16_bf16 v[32:47], v[208:211], v[102:105], v[32:47]
	ds_read_b128 v[208:211], v126 offset:23040
	v_exp_f32_e32 v72, v72
	v_exp_f32_e32 v73, v73
	v_exp_f32_e32 v74, v74
	v_exp_f32_e32 v75, v75
	s_waitcnt lgkmcnt(9)
	v_mfma_f32_32x32x16_bf16 v[0:15], v[64:67], v[220:223], v[0:15]
	ds_read_b64_tr_b16 v[220:221], v127 offset:0
	ds_read_b64_tr_b16 v[222:223], v127 offset:512
	v_add_f32_e32 v176, v72, v176
	v_add_f32_e32 v177, v73, v177
	v_cvt_pk_bf16_f32 v68, v72, v73
	v_add_f32_e32 v176, v74, v176
	v_mfma_f32_32x32x16_bf16 v[16:31], v[64:67], v[244:247], v[16:31]
	ds_read_b64_tr_b16 v[244:245], v127 offset:4096
	ds_read_b64_tr_b16 v[246:247], v127 offset:4608
	v_add_f32_e32 v177, v75, v177
	v_cvt_pk_bf16_f32 v69, v74, v75
	v_exp_f32_e32 v76, v76
	v_exp_f32_e32 v77, v77
	s_waitcnt lgkmcnt(12)
	v_mfma_f32_32x32x16_bf16 v[48:63], v[212:215], v[98:101], v[48:63]
	ds_read_b128 v[212:215], v126 offset:24576
	v_exp_f32_e32 v78, v78
	v_exp_f32_e32 v79, v79
	v_add_f32_e32 v176, v76, v176
	v_add_f32_e32 v177, v77, v177
	v_mfma_f32_32x32x16_bf16 v[32:47], v[216:219], v[98:101], v[32:47]
	ds_read_b128 v[216:219], v126 offset:25088
	v_cvt_pk_bf16_f32 v70, v76, v77
	v_add_f32_e32 v176, v78, v176
	v_add_f32_e32 v177, v79, v177
	v_cvt_pk_bf16_f32 v71, v78, v79
	s_waitcnt lgkmcnt(10)
	v_mfma_f32_32x32x16_bf16 v[0:15], v[68:71], v[240:243], v[0:15]
	v_add_f32_e32 v175, v176, v177
	v_mov_b32_e32 v178, v175
	v_add_f32_e32 v147, v147, v175
	s_nop 0
	v_mfma_f32_32x32x16_bf16 v[16:31], v[68:71], v[122:125], v[16:31]
	v_permlane32_swap_b32_e32 v175, v178
	v_add_f32_e32 v175, v175, v178
	v_cmp_lt_f32_e32 vcc, 0x43800000, v175
	s_cbranch_vccz .Lat_nr_16
	v_log_f32_e32 v175, v175
	s_nop 0
	v_max_f32_e32 v175, 0, v175
	v_exp_f32_e64 v178, -v175
	s_and_saveexec_b64 s[4:5], s[2:3]
	ds_write_b32 v143, v178 offset:40960
	s_or_b64 exec, exec, s[4:5]
	s_waitcnt lgkmcnt(0)
	v_add_u32_e32 v179, s33, v191
	v_sub_f32_e32 v224, v224, v175
	v_mul_f32_e32 v147, v147, v178
	ds_read_b128 v[80:83], v179 offset:40960
	ds_read_b128 v[84:87], v179 offset:40992
	ds_read_b128 v[88:91], v179 offset:41024
	ds_read_b128 v[92:95], v179 offset:41056
	s_waitcnt lgkmcnt(0)
	s_nop 15
	v_pk_mul_f32 v[0:1], v[0:1], v[80:81]
	v_pk_mul_f32 v[2:3], v[2:3], v[82:83]
	v_pk_mul_f32 v[4:5], v[4:5], v[84:85]
	v_pk_mul_f32 v[6:7], v[6:7], v[86:87]
	v_pk_mul_f32 v[8:9], v[8:9], v[88:89]
	v_pk_mul_f32 v[10:11], v[10:11], v[90:91]
	v_pk_mul_f32 v[12:13], v[12:13], v[92:93]
	v_pk_mul_f32 v[14:15], v[14:15], v[94:95]
	v_pk_mul_f32 v[16:17], v[16:17], v[80:81]
	v_pk_mul_f32 v[18:19], v[18:19], v[82:83]
	v_pk_mul_f32 v[20:21], v[20:21], v[84:85]
	v_pk_mul_f32 v[22:23], v[22:23], v[86:87]
	v_pk_mul_f32 v[24:25], v[24:25], v[88:89]
	v_pk_mul_f32 v[26:27], v[26:27], v[90:91]
	v_pk_mul_f32 v[28:29], v[28:29], v[92:93]
	v_pk_mul_f32 v[30:31], v[30:31], v[94:95]
	v_mov_b32_e32 v225, v224
	v_mov_b32_e32 v226, v224
	v_mov_b32_e32 v227, v224
	v_mov_b32_e32 v228, v224
	v_mov_b32_e32 v229, v224
	v_mov_b32_e32 v230, v224
	v_mov_b32_e32 v231, v224
	v_mov_b32_e32 v232, v224
	v_mov_b32_e32 v233, v224
	v_mov_b32_e32 v234, v224
	v_mov_b32_e32 v235, v224
	v_mov_b32_e32 v236, v224
	v_mov_b32_e32 v237, v224
	v_mov_b32_e32 v238, v224
	v_mov_b32_e32 v239, v224
	v_sub_f32_e32 v48, v48, v175
	v_sub_f32_e32 v49, v49, v175
	v_sub_f32_e32 v50, v50, v175
	v_sub_f32_e32 v51, v51, v175
	v_sub_f32_e32 v52, v52, v175
	v_sub_f32_e32 v53, v53, v175
	v_sub_f32_e32 v54, v54, v175
	v_sub_f32_e32 v55, v55, v175
	v_sub_f32_e32 v56, v56, v175
	v_sub_f32_e32 v57, v57, v175
	v_sub_f32_e32 v58, v58, v175
	v_sub_f32_e32 v59, v59, v175
	v_sub_f32_e32 v60, v60, v175
	v_sub_f32_e32 v61, v61, v175
	v_sub_f32_e32 v62, v62, v175
	v_sub_f32_e32 v63, v63, v175
	v_sub_f32_e32 v32, v32, v175
	v_sub_f32_e32 v33, v33, v175
	v_sub_f32_e32 v34, v34, v175
	v_sub_f32_e32 v35, v35, v175
	v_sub_f32_e32 v36, v36, v175
	v_sub_f32_e32 v37, v37, v175
	v_sub_f32_e32 v38, v38, v175
	v_sub_f32_e32 v39, v39, v175
	v_sub_f32_e32 v40, v40, v175
	v_sub_f32_e32 v41, v41, v175
	v_sub_f32_e32 v42, v42, v175
	v_sub_f32_e32 v43, v43, v175
	v_sub_f32_e32 v44, v44, v175
	v_sub_f32_e32 v45, v45, v175
	v_sub_f32_e32 v46, v46, v175
	v_sub_f32_e32 v47, v47, v175

; DEV void pvh(f32x16* o, int vb, bf16x8 pa, bf16x8 pb) {
;     s16x4 lo[4], hi[4];
; #pragma unroll
;     for (int d0 = 0; d0 < 2; ++d0)
; #pragma unroll
;         for (int kk = 0; kk < 2; ++kk) {
;             asm volatile("ds_read_b64_tr_b16 %0,%1 offset:%c2" : "=&v"(lo[d0 * 2 + kk]) : "v"(vb), "i"(d0 * 4096 + kk * 1024) : "memory");
;             asm volatile("ds_read_b64_tr_b16 %0,%1 offset:%c2" : "=&v"(hi[d0 * 2 + kk]) : "v"(vb), "i"(d0 * 4096 + kk * 1024 + 512) : "memory"); }
;     asm volatile("s_waitcnt lgkmcnt(0)" ::: "memory"); __builtin_amdgcn_sched_barrier(0);
;     ...
;     o[0] = __builtin_amdgcn_mfma_f32_32x32x16_bf16(pa, PKV(0), o[0], 0, 0, 0);
;     o[1] = __builtin_amdgcn_mfma_f32_32x32x16_bf16(pa, PKV(2), o[1], 0, 0, 0);
;     o[0] = __builtin_amdgcn_mfma_f32_32x32x16_bf16(pb, PKV(1), o[0], 0, 0, 0);
;     o[1] = __builtin_amdgcn_mfma_f32_32x32x16_bf16(pb, PKV(3), o[1], 0, 0, 0);
;     ...
; }
.Lat_k2_17:
	s_add_u32 s12, s12, 0x30000
	s_addc_u32 s13, s13, 0
	s_mov_b64 s[14:15], s[38:39]
	s_add_i32 m0, s22, 0x3000
	s_nop 0
	global_load_lds_dwordx4 v145, s[14:15]
	s_add_u32 s14, s14, 0x20000
	s_addc_u32 s15, s15, 0
	v_exp_f32_e32 v48, v48
	v_exp_f32_e32 v49, v49
	v_exp_f32_e32 v50, v50
	v_exp_f32_e32 v51, v51
	v_mov_b32_e32 v176, v48
	v_mov_b32_e32 v177, v49
	v_cvt_pk_bf16_f32 v48, v48, v49
	v_add_f32_e32 v176, v50, v176
	s_waitcnt lgkmcnt(8)
	v_mfma_f32_32x32x16_bf16 v[80:95], v[196:199], v[110:113], v[224:239]
	ds_read_b128 v[196:199], v126 offset:26624
	ds_read_b64_tr_b16 v[240:241], v127 offset:1024
	ds_read_b64_tr_b16 v[242:243], v127 offset:1536
	v_add_f32_e32 v177, v51, v177
	v_cvt_pk_bf16_f32 v49, v50, v51
	v_exp_f32_e32 v52, v52
	v_exp_f32_e32 v53, v53
	v_mfma_f32_32x32x16_bf16 v[64:79], v[200:203], v[110:113], v[224:239]
	ds_read_b128 v[200:203], v126 offset:27136
	ds_read_b64_tr_b16 v[122:123], v127 offset:5120
	ds_read_b64_tr_b16 v[124:125], v127 offset:5632
	v_exp_f32_e32 v54, v54
	v_exp_f32_e32 v55, v55
	v_add_f32_e32 v176, v52, v176
	v_add_f32_e32 v177, v53, v177
	s_waitcnt lgkmcnt(12)
	v_mfma_f32_32x32x16_bf16 v[80:95], v[204:207], v[106:109], v[80:95]
	ds_read_b128 v[204:207], v126 offset:28672
	v_cvt_pk_bf16_f32 v50, v52, v53
	v_add_f32_e32 v176, v54, v176
	v_add_f32_e32 v177, v55, v177
	v_cvt_pk_bf16_f32 v51, v54, v55
	v_mfma_f32_32x32x16_bf16 v[64:79], v[208:211], v[106:109], v[64:79]
	ds_read_b128 v[208:211], v126 offset:29184
	v_exp_f32_e32 v56, v56
	v_exp_f32_e32 v57, v57
	v_exp_f32_e32 v58, v58
	v_exp_f32_e32 v59, v59
	s_waitcnt lgkmcnt(8)
	v_mfma_f32_32x32x16_bf16 v[80:95], v[212:215], v[114:117], v[80:95]
	ds_read_b128 v[212:215], v126 offset:30720
	v_add_f32_e32 v176, v56, v176
	v_add_f32_e32 v177, v57, v177
	v_cvt_pk_bf16_f32 v52, v56, v57
	v_add_f32_e32 v176, v58, v176
	v_mfma_f32_32x32x16_bf16 v[0:15], v[48:51], v[220:223], v[0:15]
	ds_read_b64_tr_b16 v[220:221], v127 offset:2048
	ds_read_b64_tr_b16 v[222:223], v127 offset:2560
	v_add_f32_e32 v177, v59, v177
	v_cvt_pk_bf16_f32 v53, v58, v59
	v_exp_f32_e32 v60, v60
	v_exp_f32_e32 v61, v61
	v_mfma_f32_32x32x16_bf16 v[16:31], v[48:51], v[244:247], v[16:31]
	ds_read_b64_tr_b16 v[244:245], v127 offset:6144
	ds_read_b64_tr_b16 v[246:247], v127 offset:6656
	v_exp_f32_e32 v62, v62
	v_exp_f32_e32 v63, v63
	v_add_f32_e32 v176, v60, v176
	v_add_f32_e32 v177, v61, v177
	v_mfma_f32_32x32x16_bf16 v[64:79], v[216:219], v[114:117], v[64:79]
	ds_read_b128 v[216:219], v126 offset:31232
	v_cvt_pk_bf16_f32 v54, v60, v61
	v_add_f32_e32 v176, v62, v176
	v_add_f32_e32 v177, v63, v177
	v_cvt_pk_bf16_f32 v55, v62, v63
	s_waitcnt lgkmcnt(10)
	v_mfma_f32_32x32x16_bf16 v[80:95], v[196:199], v[118:121], v[80:95]
	v_exp_f32_e32 v32, v32
	v_exp_f32_e32 v33, v33
	v_exp_f32_e32 v34, v34
	v_exp_f32_e32 v35, v35
	v_mfma_f32_32x32x16_bf16 v[64:79], v[200:203], v[118:121], v[64:79]
	v_add_f32_e32 v176, v32, v176
	v_add_f32_e32 v177, v33, v177
	v_cvt_pk_bf16_f32 v32, v32, v33
	v_add_f32_e32 v176, v34, v176
	s_waitcnt lgkmcnt(8)
	v_mfma_f32_32x32x16_bf16 v[0:15], v[52:55], v[240:243], v[0:15]
	ds_read_b64_tr_b16 v[240:241], v127 offset:3072
	ds_read_b64_tr_b16 v[242:243], v127 offset:3584
	v_add_f32_e32 v177, v35, v177
	v_cvt_pk_bf16_f32 v33, v34, v35
	v_exp_f32_e32 v36, v36
	v_exp_f32_e32 v37, v37
	v_mfma_f32_32x32x16_bf16 v[16:31], v[52:55], v[122:125], v[16:31]
	ds_read_b64_tr_b16 v[122:123], v127 offset:7168
	ds_read_b64_tr_b16 v[124:125], v127 offset:7680
	v_exp_f32_e32 v38, v38
	v_exp_f32_e32 v39, v39
	v_add_f32_e32 v176, v36, v176
	v_add_f32_e32 v177, v37, v177
	s_waitcnt vmcnt(2)
	s_barrier
; DEV void pvh(f32x16* o, int vb, bf16x8 pa, bf16x8 pb) {
;     s16x4 lo[4], hi[4];
; #pragma unroll
;     for (int d0 = 0; d0 < 2; ++d0)
; #pragma unroll
;         for (int kk = 0; kk < 2; ++kk) {
;             asm volatile("ds_read_b64_tr_b16 %0,%1 offset:%c2" : "=&v"(lo[d0 * 2 + kk]) : "v"(vb), "i"(d0 * 4096 + kk * 1024) : "memory");
;             asm volatile("ds_read_b64_tr_b16 %0,%1 offset:%c2" : "=&v"(hi[d0 * 2 + kk]) : "v"(vb), "i"(d0 * 4096 + kk * 1024 + 512) : "memory"); }
;     asm volatile("s_waitcnt lgkmcnt(0)" ::: "memory"); __builtin_amdgcn_sched_barrier(0);
;     ...
;     o[0] = __builtin_amdgcn_mfma_f32_32x32x16_bf16(pa, PKV(0), o[0], 0, 0, 0);
;     o[1] = __builtin_amdgcn_mfma_f32_32x32x16_bf16(pa, PKV(2), o[1], 0, 0, 0);
;     o[0] = __builtin_amdgcn_mfma_f32_32x32x16_bf16(pb, PKV(1), o[0], 0, 0, 0);
;     o[1] = __builtin_amdgcn_mfma_f32_32x32x16_bf16(pb, PKV(3), o[1], 0, 0, 0);
;     ...
; }
	s_waitcnt lgkmcnt(10)
	v_mfma_f32_32x32x16_bf16 v[80:95], v[204:207], v[102:105], v[80:95]
	ds_read_b128 v[196:199], v194 offset:0
	ds_read_b128 v[200:203], v194 offset:512
	ds_read_b128 v[204:207], v194 offset:2048
	v_cvt_pk_bf16_f32 v34, v36, v37
	v_add_f32_e32 v176, v38, v176
	v_add_f32_e32 v177, v39, v177
	v_cvt_pk_bf16_f32 v35, v38, v39
	v_mfma_f32_32x32x16_bf16 v[64:79], v[208:211], v[102:105], v[64:79]
	ds_read_b128 v[208:211], v194 offset:2560
	v_exp_f32_e32 v40, v40
	v_exp_f32_e32 v41, v41
	v_exp_f32_e32 v42, v42
	v_exp_f32_e32 v43, v43
	s_waitcnt lgkmcnt(9)
	v_mfma_f32_32x32x16_bf16 v[0:15], v[32:35], v[220:223], v[0:15]
	ds_read_b64_tr_b16 v[220:221], v127 offset:20480
	ds_read_b64_tr_b16 v[222:223], v127 offset:20992
	v_add_f32_e32 v176, v40, v176
	v_add_f32_e32 v177, v41, v177
	v_cvt_pk_bf16_f32 v36, v40, v41
	v_add_f32_e32 v176, v42, v176
	v_mfma_f32_32x32x16_bf16 v[16:31], v[32:35], v[244:247], v[16:31]
	ds_read_b64_tr_b16 v[244:245], v127 offset:24576
	ds_read_b64_tr_b16 v[246:247], v127 offset:25088
	v_add_f32_e32 v177, v43, v177
	v_cvt_pk_bf16_f32 v37, v42, v43
	v_exp_f32_e32 v44, v44
	v_exp_f32_e32 v45, v45
	s_waitcnt lgkmcnt(12)
	v_mfma_f32_32x32x16_bf16 v[80:95], v[212:215], v[98:101], v[80:95]
	ds_read_b128 v[212:215], v194 offset:4096
	v_exp_f32_e32 v46, v46
	v_exp_f32_e32 v47, v47
	v_add_f32_e32 v176, v44, v176
	v_add_f32_e32 v177, v45, v177
	v_mfma_f32_32x32x16_bf16 v[64:79], v[216:219], v[98:101], v[64:79]
	ds_read_b128 v[216:219], v194 offset:4608
	v_cvt_pk_bf16_f32 v38, v44, v45
	v_add_f32_e32 v176, v46, v176
	v_add_f32_e32 v177, v47, v177
	v_cvt_pk_bf16_f32 v39, v46, v47
	s_waitcnt lgkmcnt(10)
	v_mfma_f32_32x32x16_bf16 v[0:15], v[36:39], v[240:243], v[0:15]
	v_add_f32_e32 v175, v176, v177
	v_mov_b32_e32 v178, v175
	v_add_f32_e32 v147, v147, v175
	s_nop 0
	v_mfma_f32_32x32x16_bf16 v[16:31], v[36:39], v[122:125], v[16:31]
	v_permlane32_swap_b32_e32 v175, v178
	v_add_f32_e32 v175, v175, v178
	v_cmp_lt_f32_e32 vcc, 0x43800000, v175
	s_cbranch_vccz .Lat_nr_18
	v_log_f32_e32 v175, v175
	s_nop 0
	v_max_f32_e32 v175, 0, v175
	v_exp_f32_e64 v178, -v175
	s_and_saveexec_b64 s[4:5], s[2:3]
	ds_write_b32 v143, v178 offset:40960
	s_or_b64 exec, exec, s[4:5]
	s_waitcnt lgkmcnt(0)
	v_add_u32_e32 v179, s33, v191
	v_sub_f32_e32 v224, v224, v175
	v_mul_f32_e32 v147, v147, v178
	ds_read_b128 v[48:51], v179 offset:40960
	ds_read_b128 v[52:55], v179 offset:40992
	ds_read_b128 v[56:59], v179 offset:41024
	ds_read_b128 v[60:63], v179 offset:41056
	s_waitcnt lgkmcnt(0)
	s_nop 15
	v_pk_mul_f32 v[0:1], v[0:1], v[48:49]
	v_pk_mul_f32 v[2:3], v[2:3], v[50:51]
	v_pk_mul_f32 v[4:5], v[4:5], v[52:53]
	v_pk_mul_f32 v[6:7], v[6:7], v[54:55]
	v_pk_mul_f32 v[8:9], v[8:9], v[56:57]
	v_pk_mul_f32 v[10:11], v[10:11], v[58:59]
	v_pk_mul_f32 v[12:13], v[12:13], v[60:61]
	v_pk_mul_f32 v[14:15], v[14:15], v[62:63]
	v_pk_mul_f32 v[16:17], v[16:17], v[48:49]
	v_pk_mul_f32 v[18:19], v[18:19], v[50:51]
	v_pk_mul_f32 v[20:21], v[20:21], v[52:53]
	v_pk_mul_f32 v[22:23], v[22:23], v[54:55]
	v_pk_mul_f32 v[24:25], v[24:25], v[56:57]
	v_pk_mul_f32 v[26:27], v[26:27], v[58:59]
	v_pk_mul_f32 v[28:29], v[28:29], v[60:61]
	v_pk_mul_f32 v[30:31], v[30:31], v[62:63]
	v_mov_b32_e32 v225, v224
	v_mov_b32_e32 v226, v224
	v_mov_b32_e32 v227, v224
	v_mov_b32_e32 v228, v224
	v_mov_b32_e32 v229, v224
	v_mov_b32_e32 v230, v224
	v_mov_b32_e32 v231, v224
	v_mov_b32_e32 v232, v224
	v_mov_b32_e32 v233, v224
	v_mov_b32_e32 v234, v224
	v_mov_b32_e32 v235, v224
	v_mov_b32_e32 v236, v224
	v_mov_b32_e32 v237, v224
	v_mov_b32_e32 v238, v224
	v_mov_b32_e32 v239, v224
	v_sub_f32_e32 v80, v80, v175
	v_sub_f32_e32 v81, v81, v175
	v_sub_f32_e32 v82, v82, v175
	v_sub_f32_e32 v83, v83, v175
	v_sub_f32_e32 v84, v84, v175
	v_sub_f32_e32 v85, v85, v175
	v_sub_f32_e32 v86, v86, v175
	v_sub_f32_e32 v87, v87, v175
	v_sub_f32_e32 v88, v88, v175
	v_sub_f32_e32 v89, v89, v175
	v_sub_f32_e32 v90, v90, v175
	v_sub_f32_e32 v91, v91, v175
	v_sub_f32_e32 v92, v92, v175
	v_sub_f32_e32 v93, v93, v175
	v_sub_f32_e32 v94, v94, v175
	v_sub_f32_e32 v95, v95, v175
	v_sub_f32_e32 v64, v64, v175
	v_sub_f32_e32 v65, v65, v175
	v_sub_f32_e32 v66, v66, v175
	v_sub_f32_e32 v67, v67, v175
	v_sub_f32_e32 v68, v68, v175
	v_sub_f32_e32 v69, v69, v175
	v_sub_f32_e32 v70, v70, v175
	v_sub_f32_e32 v71, v71, v175
	v_sub_f32_e32 v72, v72, v175
	v_sub_f32_e32 v73, v73, v175
	v_sub_f32_e32 v74, v74, v175
	v_sub_f32_e32 v75, v75, v175
	v_sub_f32_e32 v76, v76, v175
	v_sub_f32_e32 v77, v77, v175
	v_sub_f32_e32 v78, v78, v175
	v_sub_f32_e32 v79, v79, v175

; DEV void pvh(f32x16* o, int vb, bf16x8 pa, bf16x8 pb) {
;     s16x4 lo[4], hi[4];
; #pragma unroll
;     for (int d0 = 0; d0 < 2; ++d0)
; #pragma unroll
;         for (int kk = 0; kk < 2; ++kk) {
;             asm volatile("ds_read_b64_tr_b16 %0,%1 offset:%c2" : "=&v"(lo[d0 * 2 + kk]) : "v"(vb), "i"(d0 * 4096 + kk * 1024) : "memory");
;             asm volatile("ds_read_b64_tr_b16 %0,%1 offset:%c2" : "=&v"(hi[d0 * 2 + kk]) : "v"(vb), "i"(d0 * 4096 + kk * 1024 + 512) : "memory"); }
;     asm volatile("s_waitcnt lgkmcnt(0)" ::: "memory"); __builtin_amdgcn_sched_barrier(0);
;     ...
;     o[0] = __builtin_amdgcn_mfma_f32_32x32x16_bf16(pa, PKV(0), o[0], 0, 0, 0);
;     o[1] = __builtin_amdgcn_mfma_f32_32x32x16_bf16(pa, PKV(2), o[1], 0, 0, 0);
;     o[0] = __builtin_amdgcn_mfma_f32_32x32x16_bf16(pb, PKV(1), o[0], 0, 0, 0);
;     o[1] = __builtin_amdgcn_mfma_f32_32x32x16_bf16(pb, PKV(3), o[1], 0, 0, 0);
;     ...
; }
.Lat_nr_22:
	s_add_i32 m0, s22, 0x18000
	s_nop 0
	global_load_lds_dwordx4 v145, s[14:15]
	v_exp_f32_e32 v80, v80
	v_exp_f32_e32 v81, v81
	v_exp_f32_e32 v82, v82
	v_exp_f32_e32 v83, v83
	v_mov_b32_e32 v176, v80
	v_mov_b32_e32 v177, v81
	v_cvt_pk_bf16_f32 v80, v80, v81
	v_add_f32_e32 v176, v82, v176
	s_waitcnt lgkmcnt(8)
	v_mfma_f32_32x32x16_bf16 v[48:63], v[196:199], v[110:113], v[224:239]
	ds_read_b128 v[196:199], v126 offset:6144
	ds_read_b64_tr_b16 v[240:241], v139 offset:21504
	ds_read_b64_tr_b16 v[242:243], v139 offset:22016
	v_add_f32_e32 v177, v83, v177
	v_cvt_pk_bf16_f32 v81, v82, v83
	v_exp_f32_e32 v84, v84
	v_exp_f32_e32 v85, v85
	v_mfma_f32_32x32x16_bf16 v[32:47], v[200:203], v[110:113], v[224:239]
	ds_read_b128 v[200:203], v126 offset:6656
	ds_read_b64_tr_b16 v[122:123], v139 offset:25600
	ds_read_b64_tr_b16 v[124:125], v139 offset:26112
	v_exp_f32_e32 v86, v86
	v_exp_f32_e32 v87, v87
	v_add_f32_e32 v176, v84, v176
	v_add_f32_e32 v177, v85, v177
	s_waitcnt lgkmcnt(12)
	v_mfma_f32_32x32x16_bf16 v[48:63], v[204:207], v[106:109], v[48:63]
	ds_read_b128 v[204:207], v126 offset:8192
	v_cvt_pk_bf16_f32 v82, v84, v85
	v_add_f32_e32 v176, v86, v176
	v_add_f32_e32 v177, v87, v177
	v_cvt_pk_bf16_f32 v83, v86, v87
	v_mfma_f32_32x32x16_bf16 v[32:47], v[208:211], v[106:109], v[32:47]
	ds_read_b128 v[208:211], v126 offset:8704
	v_exp_f32_e32 v88, v88
	v_exp_f32_e32 v89, v89
	v_exp_f32_e32 v90, v90
	v_exp_f32_e32 v91, v91
	s_waitcnt lgkmcnt(8)
	v_mfma_f32_32x32x16_bf16 v[48:63], v[212:215], v[114:117], v[48:63]
	ds_read_b128 v[212:215], v126 offset:10240
	v_add_f32_e32 v176, v88, v176
	v_add_f32_e32 v177, v89, v177
	v_cvt_pk_bf16_f32 v84, v88, v89
	v_add_f32_e32 v176, v90, v176
	v_mfma_f32_32x32x16_bf16 v[0:15], v[80:83], v[220:223], v[0:15]
	ds_read_b64_tr_b16 v[220:221], v139 offset:22528
	ds_read_b64_tr_b16 v[222:223], v139 offset:23040
	v_add_f32_e32 v177, v91, v177
	v_cvt_pk_bf16_f32 v85, v90, v91
	v_exp_f32_e32 v92, v92
	v_exp_f32_e32 v93, v93
	v_mfma_f32_32x32x16_bf16 v[16:31], v[80:83], v[244:247], v[16:31]
	ds_read_b64_tr_b16 v[244:245], v139 offset:26624
	ds_read_b64_tr_b16 v[246:247], v139 offset:27136
	v_exp_f32_e32 v94, v94
	v_exp_f32_e32 v95, v95
	v_add_f32_e32 v176, v92, v176
	v_add_f32_e32 v177, v93, v177
	v_mfma_f32_32x32x16_bf16 v[32:47], v[216:219], v[114:117], v[32:47]
	ds_read_b128 v[216:219], v126 offset:10752
	v_cvt_pk_bf16_f32 v86, v92, v93
	v_add_f32_e32 v176, v94, v176
	v_add_f32_e32 v177, v95, v177
	v_cvt_pk_bf16_f32 v87, v94, v95
	s_waitcnt lgkmcnt(10)
	v_mfma_f32_32x32x16_bf16 v[48:63], v[196:199], v[118:121], v[48:63]
	v_exp_f32_e32 v64, v64
	v_exp_f32_e32 v65, v65
	v_exp_f32_e32 v66, v66
	v_exp_f32_e32 v67, v67
	v_mfma_f32_32x32x16_bf16 v[32:47], v[200:203], v[118:121], v[32:47]
	v_add_f32_e32 v176, v64, v176
	v_add_f32_e32 v177, v65, v177
	v_cvt_pk_bf16_f32 v64, v64, v65
	v_add_f32_e32 v176, v66, v176
	s_waitcnt lgkmcnt(8)
	v_mfma_f32_32x32x16_bf16 v[0:15], v[84:87], v[240:243], v[0:15]
	ds_read_b64_tr_b16 v[240:241], v139 offset:23552
	ds_read_b64_tr_b16 v[242:243], v139 offset:24064
	v_add_f32_e32 v177, v67, v177
	v_cvt_pk_bf16_f32 v65, v66, v67
	v_exp_f32_e32 v68, v68
	v_exp_f32_e32 v69, v69
	v_mfma_f32_32x32x16_bf16 v[16:31], v[84:87], v[122:125], v[16:31]
	ds_read_b64_tr_b16 v[122:123], v139 offset:27648
	ds_read_b64_tr_b16 v[124:125], v139 offset:28160
	v_exp_f32_e32 v70, v70
	v_exp_f32_e32 v71, v71
	v_add_f32_e32 v176, v68, v176
	v_add_f32_e32 v177, v69, v177
	s_waitcnt vmcnt(1)
	s_barrier
	s_waitcnt lgkmcnt(10)
	v_mfma_f32_32x32x16_bf16 v[48:63], v[204:207], v[102:105], v[48:63]
	ds_read_b128 v[196:199], v126 offset:20480
	ds_read_b128 v[200:203], v126 offset:20992
	ds_read_b128 v[204:207], v126 offset:22528
	v_cvt_pk_bf16_f32 v66, v68, v69
	v_add_f32_e32 v176, v70, v176
	v_add_f32_e32 v177, v71, v177
	v_cvt_pk_bf16_f32 v67, v70, v71
	v_mfma_f32_32x32x16_bf16 v[32:47], v[208:211], v[102:105], v[32:47]
	ds_read_b128 v[208:211], v126 offset:23040
	v_exp_f32_e32 v72, v72
	v_exp_f32_e32 v73, v73
	v_exp_f32_e32 v74, v74
	v_exp_f32_e32 v75, v75
	s_waitcnt lgkmcnt(9)
	v_mfma_f32_32x32x16_bf16 v[0:15], v[64:67], v[220:223], v[0:15]
	ds_read_b64_tr_b16 v[220:221], v127 offset:0
	ds_read_b64_tr_b16 v[222:223], v127 offset:512
	v_add_f32_e32 v176, v72, v176
	v_add_f32_e32 v177, v73, v177
	v_cvt_pk_bf16_f32 v68, v72, v73
	v_add_f32_e32 v176, v74, v176
	v_mfma_f32_32x32x16_bf16 v[16:31], v[64:67], v[244:247], v[16:31]
	ds_read_b64_tr_b16 v[244:245], v127 offset:4096
	ds_read_b64_tr_b16 v[246:247], v127 offset:4608
	v_add_f32_e32 v177, v75, v177
	v_cvt_pk_bf16_f32 v69, v74, v75
	v_exp_f32_e32 v76, v76
	v_exp_f32_e32 v77, v77
	s_waitcnt lgkmcnt(12)
	v_mfma_f32_32x32x16_bf16 v[48:63], v[212:215], v[98:101], v[48:63]
	ds_read_b128 v[212:215], v126 offset:24576
	v_exp_f32_e32 v78, v78
	v_exp_f32_e32 v79, v79
	v_add_f32_e32 v176, v76, v176
	v_add_f32_e32 v177, v77, v177
	v_mfma_f32_32x32x16_bf16 v[32:47], v[216:219], v[98:101], v[32:47]
	ds_read_b128 v[216:219], v126 offset:25088
	v_cvt_pk_bf16_f32 v70, v76, v77
	v_add_f32_e32 v176, v78, v176
	v_add_f32_e32 v177, v79, v177
	v_cvt_pk_bf16_f32 v71, v78, v79
	s_waitcnt lgkmcnt(10)
	v_mfma_f32_32x32x16_bf16 v[0:15], v[68:71], v[240:243], v[0:15]
	v_add_f32_e32 v175, v176, v177
	v_mov_b32_e32 v178, v175
	v_add_f32_e32 v147, v147, v175
	s_nop 0
	v_mfma_f32_32x32x16_bf16 v[16:31], v[68:71], v[122:125], v[16:31]
	v_permlane32_swap_b32_e32 v175, v178
	v_add_f32_e32 v175, v175, v178
	v_cmp_lt_f32_e32 vcc, 0x43800000, v175
	s_cbranch_vccz .Lat_nr_23
; DEV void pvh(f32x16* o, int vb, bf16x8 pa, bf16x8 pb) {
;     s16x4 lo[4], hi[4];
; #pragma unroll
;     for (int d0 = 0; d0 < 2; ++d0)
; #pragma unroll
;         for (int kk = 0; kk < 2; ++kk) {
;             asm volatile("ds_read_b64_tr_b16 %0,%1 offset:%c2" : "=&v"(lo[d0 * 2 + kk]) : "v"(vb), "i"(d0 * 4096 + kk * 1024) : "memory");
;             asm volatile("ds_read_b64_tr_b16 %0,%1 offset:%c2" : "=&v"(hi[d0 * 2 + kk]) : "v"(vb), "i"(d0 * 4096 + kk * 1024 + 512) : "memory"); }
;     asm volatile("s_waitcnt lgkmcnt(0)" ::: "memory"); __builtin_amdgcn_sched_barrier(0);
;     ...
;     o[0] = __builtin_amdgcn_mfma_f32_32x32x16_bf16(pa, PKV(0), o[0], 0, 0, 0);
;     o[1] = __builtin_amdgcn_mfma_f32_32x32x16_bf16(pa, PKV(2), o[1], 0, 0, 0);
;     o[0] = __builtin_amdgcn_mfma_f32_32x32x16_bf16(pb, PKV(1), o[0], 0, 0, 0);
;     o[1] = __builtin_amdgcn_mfma_f32_32x32x16_bf16(pb, PKV(3), o[1], 0, 0, 0);
;     ...
; }
	v_log_f32_e32 v175, v175
	s_nop 0
	v_max_f32_e32 v175, 0, v175
	v_exp_f32_e64 v178, -v175
	s_and_saveexec_b64 s[4:5], s[2:3]
	ds_write_b32 v143, v178 offset:40960
	s_or_b64 exec, exec, s[4:5]
	s_waitcnt lgkmcnt(0)
	v_add_u32_e32 v179, s33, v191
	v_sub_f32_e32 v224, v224, v175
	v_mul_f32_e32 v147, v147, v178
	ds_read_b128 v[80:83], v179 offset:40960
	ds_read_b128 v[84:87], v179 offset:40992
	ds_read_b128 v[88:91], v179 offset:41024
	ds_read_b128 v[92:95], v179 offset:41056
	s_waitcnt lgkmcnt(0)
	s_nop 15
	v_pk_mul_f32 v[0:1], v[0:1], v[80:81]
	v_pk_mul_f32 v[2:3], v[2:3], v[82:83]
	v_pk_mul_f32 v[4:5], v[4:5], v[84:85]
	v_pk_mul_f32 v[6:7], v[6:7], v[86:87]
	v_pk_mul_f32 v[8:9], v[8:9], v[88:89]
	v_pk_mul_f32 v[10:11], v[10:11], v[90:91]
	v_pk_mul_f32 v[12:13], v[12:13], v[92:93]
	v_pk_mul_f32 v[14:15], v[14:15], v[94:95]
	v_pk_mul_f32 v[16:17], v[16:17], v[80:81]
	v_pk_mul_f32 v[18:19], v[18:19], v[82:83]
	v_pk_mul_f32 v[20:21], v[20:21], v[84:85]
	v_pk_mul_f32 v[22:23], v[22:23], v[86:87]
	v_pk_mul_f32 v[24:25], v[24:25], v[88:89]
	v_pk_mul_f32 v[26:27], v[26:27], v[90:91]
	v_pk_mul_f32 v[28:29], v[28:29], v[92:93]
	v_pk_mul_f32 v[30:31], v[30:31], v[94:95]
	v_mov_b32_e32 v225, v224
	v_mov_b32_e32 v226, v224
	v_mov_b32_e32 v227, v224
	v_mov_b32_e32 v228, v224
	v_mov_b32_e32 v229, v224
	v_mov_b32_e32 v230, v224
	v_mov_b32_e32 v231, v224
	v_mov_b32_e32 v232, v224
	v_mov_b32_e32 v233, v224
	v_mov_b32_e32 v234, v224
	v_mov_b32_e32 v235, v224
	v_mov_b32_e32 v236, v224
	v_mov_b32_e32 v237, v224
	v_mov_b32_e32 v238, v224
	v_mov_b32_e32 v239, v224
	v_sub_f32_e32 v48, v48, v175
	v_sub_f32_e32 v49, v49, v175
	v_sub_f32_e32 v50, v50, v175
	v_sub_f32_e32 v51, v51, v175
	v_sub_f32_e32 v52, v52, v175
	v_sub_f32_e32 v53, v53, v175
	v_sub_f32_e32 v54, v54, v175
	v_sub_f32_e32 v55, v55, v175
	v_sub_f32_e32 v56, v56, v175
	v_sub_f32_e32 v57, v57, v175
	v_sub_f32_e32 v58, v58, v175
	v_sub_f32_e32 v59, v59, v175
	v_sub_f32_e32 v60, v60, v175
	v_sub_f32_e32 v61, v61, v175
	v_sub_f32_e32 v62, v62, v175
	v_sub_f32_e32 v63, v63, v175
	v_sub_f32_e32 v32, v32, v175
	v_sub_f32_e32 v33, v33, v175
	v_sub_f32_e32 v34, v34, v175
	v_sub_f32_e32 v35, v35, v175
	v_sub_f32_e32 v36, v36, v175
	v_sub_f32_e32 v37, v37, v175
	v_sub_f32_e32 v38, v38, v175
	v_sub_f32_e32 v39, v39, v175
	v_sub_f32_e32 v40, v40, v175
	v_sub_f32_e32 v41, v41, v175
	v_sub_f32_e32 v42, v42, v175
	v_sub_f32_e32 v43, v43, v175
	v_sub_f32_e32 v44, v44, v175
	v_sub_f32_e32 v45, v45, v175
	v_sub_f32_e32 v46, v46, v175
	v_sub_f32_e32 v47, v47, v175
.Lat_nr_23:
	v_exp_f32_e32 v48, v48
	v_exp_f32_e32 v49, v49
	v_exp_f32_e32 v50, v50
	v_exp_f32_e32 v51, v51
	v_mov_b32_e32 v176, v48
	v_mov_b32_e32 v177, v49
	v_cvt_pk_bf16_f32 v48, v48, v49
	v_add_f32_e32 v176, v50, v176
	s_waitcnt lgkmcnt(8)
	v_mfma_f32_32x32x16_bf16 v[80:95], v[196:199], v[110:113], v[224:239]
	ds_read_b128 v[196:199], v126 offset:26624
	ds_read_b64_tr_b16 v[240:241], v127 offset:1024
	ds_read_b64_tr_b16 v[242:243], v127 offset:1536
	v_add_f32_e32 v177, v51, v177
	v_cvt_pk_bf16_f32 v49, v50, v51
	v_exp_f32_e32 v52, v52
	v_exp_f32_e32 v53, v53
	v_mfma_f32_32x32x16_bf16 v[64:79], v[200:203], v[110:113], v[224:239]
	ds_read_b128 v[200:203], v126 offset:27136
	ds_read_b64_tr_b16 v[122:123], v127 offset:5120
	ds_read_b64_tr_b16 v[124:125], v127 offset:5632
	v_exp_f32_e32 v54, v54
	v_exp_f32_e32 v55, v55
	v_add_f32_e32 v176, v52, v176
	v_add_f32_e32 v177, v53, v177
	s_waitcnt lgkmcnt(12)
	v_mfma_f32_32x32x16_bf16 v[80:95], v[204:207], v[106:109], v[80:95]
	ds_read_b128 v[204:207], v126 offset:28672
	v_cvt_pk_bf16_f32 v50, v52, v53
	v_add_f32_e32 v176, v54, v176
	v_add_f32_e32 v177, v55, v177
	v_cvt_pk_bf16_f32 v51, v54, v55
	v_mfma_f32_32x32x16_bf16 v[64:79], v[208:211], v[106:109], v[64:79]
	ds_read_b128 v[208:211], v126 offset:29184
	v_exp_f32_e32 v56, v56
	v_exp_f32_e32 v57, v57
	v_exp_f32_e32 v58, v58
	v_exp_f32_e32 v59, v59
	s_waitcnt lgkmcnt(8)
	v_mfma_f32_32x32x16_bf16 v[80:95], v[212:215], v[114:117], v[80:95]
	ds_read_b128 v[212:215], v126 offset:30720
	v_add_f32_e32 v176, v56, v176
	v_add_f32_e32 v177, v57, v177
	v_cvt_pk_bf16_f32 v52, v56, v57
	v_add_f32_e32 v176, v58, v176
	v_mfma_f32_32x32x16_bf16 v[0:15], v[48:51], v[220:223], v[0:15]
	ds_read_b64_tr_b16 v[220:221], v127 offset:2048
	ds_read_b64_tr_b16 v[222:223], v127 offset:2560
	v_add_f32_e32 v177, v59, v177
	v_cvt_pk_bf16_f32 v53, v58, v59
	v_exp_f32_e32 v60, v60
	v_exp_f32_e32 v61, v61
	v_mfma_f32_32x32x16_bf16 v[16:31], v[48:51], v[244:247], v[16:31]
	ds_read_b64_tr_b16 v[244:245], v127 offset:6144
	ds_read_b64_tr_b16 v[246:247], v127 offset:6656
	v_exp_f32_e32 v62, v62
	v_exp_f32_e32 v63, v63
	v_add_f32_e32 v176, v60, v176
	v_add_f32_e32 v177, v61, v177
	v_mfma_f32_32x32x16_bf16 v[64:79], v[216:219], v[114:117], v[64:79]
	ds_read_b128 v[216:219], v126 offset:31232
	v_cvt_pk_bf16_f32 v54, v60, v61
	v_add_f32_e32 v176, v62, v176
	v_add_f32_e32 v177, v63, v177
	v_cvt_pk_bf16_f32 v55, v62, v63
	s_waitcnt lgkmcnt(10)
	v_mfma_f32_32x32x16_bf16 v[80:95], v[196:199], v[118:121], v[80:95]
	v_exp_f32_e32 v32, v32
	v_exp_f32_e32 v33, v33
	v_exp_f32_e32 v34, v34
	v_exp_f32_e32 v35, v35
	v_mfma_f32_32x32x16_bf16 v[64:79], v[200:203], v[118:121], v[64:79]
	v_add_f32_e32 v176, v32, v176
	v_add_f32_e32 v177, v33, v177
	v_cvt_pk_bf16_f32 v32, v32, v33
	v_add_f32_e32 v176, v34, v176
	s_waitcnt lgkmcnt(8)
	v_mfma_f32_32x32x16_bf16 v[0:15], v[52:55], v[240:243], v[0:15]
	ds_read_b64_tr_b16 v[240:241], v127 offset:3072
	ds_read_b64_tr_b16 v[242:243], v127 offset:3584
	v_add_f32_e32 v177, v35, v177
	v_cvt_pk_bf16_f32 v33, v34, v35
	v_exp_f32_e32 v36, v36
	v_exp_f32_e32 v37, v37
	v_mfma_f32_32x32x16_bf16 v[16:31], v[52:55], v[122:125], v[16:31]
	ds_read_b64_tr_b16 v[122:123], v127 offset:7168
	ds_read_b64_tr_b16 v[124:125], v127 offset:7680
	v_exp_f32_e32 v38, v38
	v_exp_f32_e32 v39, v39
	v_add_f32_e32 v176, v36, v176
	v_add_f32_e32 v177, v37, v177
	s_waitcnt vmcnt(0)
	s_barrier
	s_waitcnt lgkmcnt(10)
	v_mfma_f32_32x32x16_bf16 v[80:95], v[204:207], v[102:105], v[80:95]
	v_cvt_pk_bf16_f32 v34, v36, v37
	v_add_f32_e32 v176, v38, v176
	v_add_f32_e32 v177, v39, v177
	v_cvt_pk_bf16_f32 v35, v38, v39
	v_mfma_f32_32x32x16_bf16 v[64:79], v[208:211], v[102:105], v[64:79]
	v_exp_f32_e32 v40, v40
	v_exp_f32_e32 v41, v41
	v_exp_f32_e32 v42, v42
	v_exp_f32_e32 v43, v43
	s_waitcnt lgkmcnt(5)
	v_mfma_f32_32x32x16_bf16 v[0:15], v[32:35], v[220:223], v[0:15]
	ds_read_b64_tr_b16 v[220:221], v127 offset:20480
	ds_read_b64_tr_b16 v[222:223], v127 offset:20992
	v_add_f32_e32 v176, v40, v176
	v_add_f32_e32 v177, v41, v177
	v_cvt_pk_bf16_f32 v36, v40, v41
	v_add_f32_e32 v176, v42, v176
	v_mfma_f32_32x32x16_bf16 v[16:31], v[32:35], v[244:247], v[16:31]
	ds_read_b64_tr_b16 v[244:245], v127 offset:24576
	ds_read_b64_tr_b16 v[246:247], v127 offset:25088
	v_add_f32_e32 v177, v43, v177
	v_cvt_pk_bf16_f32 v37, v42, v43
	v_exp_f32_e32 v44, v44
	v_exp_f32_e32 v45, v45
	s_waitcnt lgkmcnt(8)
	v_mfma_f32_32x32x16_bf16 v[80:95], v[212:215], v[98:101], v[80:95]
	v_exp_f32_e32 v46, v46
	v_exp_f32_e32 v47, v47
	v_add_f32_e32 v176, v44, v176
	v_add_f32_e32 v177, v45, v177
	v_mfma_f32_32x32x16_bf16 v[64:79], v[216:219], v[98:101], v[64:79]
	v_cvt_pk_bf16_f32 v38, v44, v45
	v_add_f32_e32 v176, v46, v176
	v_add_f32_e32 v177, v47, v177
	v_cvt_pk_bf16_f32 v39, v46, v47
	s_waitcnt lgkmcnt(4)
	v_mfma_f32_32x32x16_bf16 v[0:15], v[36:39], v[240:243], v[0:15]
	v_add_f32_e32 v175, v176, v177
	v_mov_b32_e32 v178, v175
	v_add_f32_e32 v147, v147, v175
	s_nop 0
	v_mfma_f32_32x32x16_bf16 v[16:31], v[36:39], v[122:125], v[16:31]
	v_permlane32_swap_b32_e32 v175, v178
	v_add_f32_e32 v175, v175, v178
	v_cmp_lt_f32_e32 vcc, 0x43800000, v175
	s_cbranch_vccz .Lat_nr_24
	v_log_f32_e32 v175, v175
	s_nop 0
	v_max_f32_e32 v175, 0, v175
	v_exp_f32_e64 v178, -v175
	s_and_saveexec_b64 s[4:5], s[2:3]
	ds_write_b32 v143, v178 offset:40960
	s_or_b64 exec, exec, s[4:5]
	s_waitcnt lgkmcnt(0)
	v_add_u32_e32 v179, s33, v191
	v_sub_f32_e32 v224, v224, v175
	v_mul_f32_e32 v147, v147, v178
	ds_read_b128 v[48:51], v179 offset:40960
	ds_read_b128 v[52:55], v179 offset:40992
	ds_read_b128 v[56:59], v179 offset:41024
	ds_read_b128 v[60:63], v179 offset:41056
	s_waitcnt lgkmcnt(0)
	s_nop 15
	v_pk_mul_f32 v[0:1], v[0:1], v[48:49]
	v_pk_mul_f32 v[2:3], v[2:3], v[50:51]
	v_pk_mul_f32 v[4:5], v[4:5], v[52:53]
	v_pk_mul_f32 v[6:7], v[6:7], v[54:55]
	v_pk_mul_f32 v[8:9], v[8:9], v[56:57]
	v_pk_mul_f32 v[10:11], v[10:11], v[58:59]
	v_pk_mul_f32 v[12:13], v[12:13], v[60:61]
	v_pk_mul_f32 v[14:15], v[14:15], v[62:63]
	v_pk_mul_f32 v[16:17], v[16:17], v[48:49]
	v_pk_mul_f32 v[18:19], v[18:19], v[50:51]
	v_pk_mul_f32 v[20:21], v[20:21], v[52:53]
	v_pk_mul_f32 v[22:23], v[22:23], v[54:55]
	v_pk_mul_f32 v[24:25], v[24:25], v[56:57]
	v_pk_mul_f32 v[26:27], v[26:27], v[58:59]
	v_pk_mul_f32 v[28:29], v[28:29], v[60:61]
	v_pk_mul_f32 v[30:31], v[30:31], v[62:63]
	v_mov_b32_e32 v225, v224
	v_mov_b32_e32 v226, v224
	v_mov_b32_e32 v227, v224
	v_mov_b32_e32 v228, v224
	v_mov_b32_e32 v229, v224
	v_mov_b32_e32 v230, v224
	v_mov_b32_e32 v231, v224
	v_mov_b32_e32 v232, v224
	v_mov_b32_e32 v233, v224
	v_mov_b32_e32 v234, v224
	v_mov_b32_e32 v235, v224
	v_mov_b32_e32 v236, v224
	v_mov_b32_e32 v237, v224
	v_mov_b32_e32 v238, v224
	v_mov_b32_e32 v239, v224
	v_sub_f32_e32 v80, v80, v175
	v_sub_f32_e32 v81, v81, v175
	v_sub_f32_e32 v82, v82, v175
	v_sub_f32_e32 v83, v83, v175
	v_sub_f32_e32 v84, v84, v175
	v_sub_f32_e32 v85, v85, v175
	v_sub_f32_e32 v86, v86, v175
	v_sub_f32_e32 v87, v87, v175
	v_sub_f32_e32 v88, v88, v175
	v_sub_f32_e32 v89, v89, v175
	v_sub_f32_e32 v90, v90, v175
	v_sub_f32_e32 v91, v91, v175
	v_sub_f32_e32 v92, v92, v175
	v_sub_f32_e32 v93, v93, v175
	v_sub_f32_e32 v94, v94, v175
	v_sub_f32_e32 v95, v95, v175
	v_sub_f32_e32 v64, v64, v175
	v_sub_f32_e32 v65, v65, v175
	v_sub_f32_e32 v66, v66, v175
	v_sub_f32_e32 v67, v67, v175
	v_sub_f32_e32 v68, v68, v175
	v_sub_f32_e32 v69, v69, v175
	v_sub_f32_e32 v70, v70, v175
	v_sub_f32_e32 v71, v71, v175
	v_sub_f32_e32 v72, v72, v175
	v_sub_f32_e32 v73, v73, v175
	v_sub_f32_e32 v74, v74, v175
	v_sub_f32_e32 v75, v75, v175
	v_sub_f32_e32 v76, v76, v175
	v_sub_f32_e32 v77, v77, v175
	v_sub_f32_e32 v78, v78, v175
	v_sub_f32_e32 v79, v79, v175
.Lat_nr_24:
	v_exp_f32_e32 v80, v80
	v_exp_f32_e32 v81, v81
	v_exp_f32_e32 v82, v82
	v_exp_f32_e32 v83, v83
	v_mov_b32_e32 v176, v80
	v_mov_b32_e32 v177, v81
	v_cvt_pk_bf16_f32 v80, v80, v81
	v_add_f32_e32 v176, v82, v176
	ds_read_b64_tr_b16 v[240:241], v127 offset:21504
	ds_read_b64_tr_b16 v[242:243], v127 offset:22016
	v_add_f32_e32 v177, v83, v177
	v_cvt_pk_bf16_f32 v81, v82, v83
	v_exp_f32_e32 v84, v84
	v_exp_f32_e32 v85, v85
	ds_read_b64_tr_b16 v[122:123], v127 offset:25600
	ds_read_b64_tr_b16 v[124:125], v127 offset:26112
	v_exp_f32_e32 v86, v86
	v_exp_f32_e32 v87, v87
	v_add_f32_e32 v176, v84, v176
	v_add_f32_e32 v177, v85, v177
	v_cvt_pk_bf16_f32 v82, v84, v85
	v_add_f32_e32 v176, v86, v176
	v_add_f32_e32 v177, v87, v177
	v_cvt_pk_bf16_f32 v83, v86, v87
	v_exp_f32_e32 v88, v88
	v_exp_f32_e32 v89, v89
	v_exp_f32_e32 v90, v90
	v_exp_f32_e32 v91, v91
	v_add_f32_e32 v176, v88, v176
	v_add_f32_e32 v177, v89, v177
	v_cvt_pk_bf16_f32 v84, v88, v89
	v_add_f32_e32 v176, v90, v176
	s_waitcnt lgkmcnt(4)
	v_mfma_f32_32x32x16_bf16 v[0:15], v[80:83], v[220:223], v[0:15]
	ds_read_b64_tr_b16 v[220:221], v127 offset:22528
	ds_read_b64_tr_b16 v[222:223], v127 offset:23040
	v_add_f32_e32 v177, v91, v177
	v_cvt_pk_bf16_f32 v85, v90, v91
	v_exp_f32_e32 v92, v92
	v_exp_f32_e32 v93, v93
	v_mfma_f32_32x32x16_bf16 v[16:31], v[80:83], v[244:247], v[16:31]
	ds_read_b64_tr_b16 v[244:245], v127 offset:26624
	ds_read_b64_tr_b16 v[246:247], v127 offset:27136
	v_exp_f32_e32 v94, v94
	v_exp_f32_e32 v95, v95
	v_add_f32_e32 v176, v92, v176
	v_add_f32_e32 v177, v93, v177
	v_cvt_pk_bf16_f32 v86, v92, v93
	v_add_f32_e32 v176, v94, v176
	v_add_f32_e32 v177, v95, v177
	v_cvt_pk_bf16_f32 v87, v94, v95
	v_exp_f32_e32 v64, v64
	v_exp_f32_e32 v65, v65
	v_exp_f32_e32 v66, v66
	v_exp_f32_e32 v67, v67
	v_add_f32_e32 v176, v64, v176
	v_add_f32_e32 v177, v65, v177
	v_cvt_pk_bf16_f32 v64, v64, v65
	v_add_f32_e32 v176, v66, v176
	s_waitcnt lgkmcnt(4)
	v_mfma_f32_32x32x16_bf16 v[0:15], v[84:87], v[240:243], v[0:15]
	ds_read_b64_tr_b16 v[240:241], v127 offset:23552
	ds_read_b64_tr_b16 v[242:243], v127 offset:24064
	v_add_f32_e32 v177, v67, v177
	v_cvt_pk_bf16_f32 v65, v66, v67
	v_exp_f32_e32 v68, v68
	v_exp_f32_e32 v69, v69
	v_mfma_f32_32x32x16_bf16 v[16:31], v[84:87], v[122:125], v[16:31]
	ds_read_b64_tr_b16 v[122:123], v127 offset:27648
	ds_read_b64_tr_b16 v[124:125], v127 offset:28160
	v_exp_f32_e32 v70, v70
	v_exp_f32_e32 v71, v71
	v_add_f32_e32 v176, v68, v176
	v_add_f32_e32 v177, v69, v177
	s_waitcnt vmcnt(0)
	s_barrier
	v_cvt_pk_bf16_f32 v66, v68, v69
	v_add_f32_e32 v176, v70, v176
	v_add_f32_e32 v177, v71, v177
	v_cvt_pk_bf16_f32 v67, v70, v71
	v_exp_f32_e32 v72, v72
	v_exp_f32_e32 v73, v73
	v_exp_f32_e32 v74, v74
	v_exp_f32_e32 v75, v75
	s_waitcnt lgkmcnt(4)
	v_mfma_f32_32x32x16_bf16 v[0:15], v[64:67], v[220:223], v[0:15]
	v_add_f32_e32 v176, v72, v176
	v_add_f32_e32 v177, v73, v177
	v_cvt_pk_bf16_f32 v68, v72, v73
	v_add_f32_e32 v176, v74, v176
	v_mfma_f32_32x32x16_bf16 v[16:31], v[64:67], v[244:247], v[16:31]
	v_add_f32_e32 v177, v75, v177
	v_cvt_pk_bf16_f32 v69, v74, v75
	v_exp_f32_e32 v76, v76
	v_exp_f32_e32 v77, v77
	v_exp_f32_e32 v78, v78
	v_exp_f32_e32 v79, v79
	v_add_f32_e32 v176, v76, v176
	v_add_f32_e32 v177, v77, v177
	v_cvt_pk_bf16_f32 v70, v76, v77
	v_add_f32_e32 v176, v78, v176
	v_add_f32_e32 v177, v79, v177
	v_cvt_pk_bf16_f32 v71, v78, v79
	s_waitcnt lgkmcnt(0)
	v_mfma_f32_32x32x16_bf16 v[0:15], v[68:71], v[240:243], v[0:15]
	v_add_f32_e32 v175, v176, v177
	v_mov_b32_e32 v178, v175
	v_add_f32_e32 v147, v147, v175
	s_nop 0
	v_mfma_f32_32x32x16_bf16 v[16:31], v[68:71], v[122:125], v[16:31]
	v_permlane32_swap_b32_e32 v175, v178
	v_add_f32_e32 v175, v175, v178
	v_cmp_lt_f32_e32 vcc, 0x43800000, v175
	s_cbranch_vccz .Lat_nr_25
	v_log_f32_e32 v175, v175
	s_nop 0
	v_max_f32_e32 v175, 0, v175
	v_exp_f32_e64 v178, -v175
	s_and_saveexec_b64 s[4:5], s[2:3]
	ds_write_b32 v143, v178 offset:40960
	s_or_b64 exec, exec, s[4:5]
	s_waitcnt lgkmcnt(0)
	v_add_u32_e32 v179, s33, v191
	v_sub_f32_e32 v224, v224, v175
	v_mul_f32_e32 v147, v147, v178
	ds_read_b128 v[80:83], v179 offset:40960
	ds_read_b128 v[84:87], v179 offset:40992
	ds_read_b128 v[88:91], v179 offset:41024
	ds_read_b128 v[92:95], v179 offset:41056
	s_waitcnt lgkmcnt(0)
	s_nop 15
	v_pk_mul_f32 v[0:1], v[0:1], v[80:81]
	v_pk_mul_f32 v[2:3], v[2:3], v[82:83]
	v_pk_mul_f32 v[4:5], v[4:5], v[84:85]
	v_pk_mul_f32 v[6:7], v[6:7], v[86:87]
	v_pk_mul_f32 v[8:9], v[8:9], v[88:89]
	v_pk_mul_f32 v[10:11], v[10:11], v[90:91]
	v_pk_mul_f32 v[12:13], v[12:13], v[92:93]
	v_pk_mul_f32 v[14:15], v[14:15], v[94:95]
	v_pk_mul_f32 v[16:17], v[16:17], v[80:81]
	v_pk_mul_f32 v[18:19], v[18:19], v[82:83]
	v_pk_mul_f32 v[20:21], v[20:21], v[84:85]
	v_pk_mul_f32 v[22:23], v[22:23], v[86:87]
	v_pk_mul_f32 v[24:25], v[24:25], v[88:89]
	v_pk_mul_f32 v[26:27], v[26:27], v[90:91]
	v_pk_mul_f32 v[28:29], v[28:29], v[92:93]
	v_pk_mul_f32 v[30:31], v[30:31], v[94:95]
	v_mov_b32_e32 v225, v224
	v_mov_b32_e32 v226, v224
	v_mov_b32_e32 v227, v224
	v_mov_b32_e32 v228, v224
	v_mov_b32_e32 v229, v224
	v_mov_b32_e32 v230, v224
	v_mov_b32_e32 v231, v224
	v_mov_b32_e32 v232, v224
	v_mov_b32_e32 v233, v224
	v_mov_b32_e32 v234, v224
	v_mov_b32_e32 v235, v224
	v_mov_b32_e32 v236, v224
	v_mov_b32_e32 v237, v224
	v_mov_b32_e32 v238, v224
	v_mov_b32_e32 v239, v224

; DEV void grid_barrier(unsigned* cnt, const unsigned target, const int tid) {
;     asm volatile("s_waitcnt vmcnt(0)" ::: "memory");
;     __syncthreads();
;     if (tid == 0) {
;         __builtin_amdgcn_fence(__ATOMIC_RELEASE, "agent");
;         __hip_atomic_fetch_add(cnt, 1u, __ATOMIC_RELAXED, __HIP_MEMORY_SCOPE_AGENT);
;         while (__hip_atomic_load(cnt, __ATOMIC_RELAXED, __HIP_MEMORY_SCOPE_AGENT) < target) __builtin_amdgcn_s_sleep(28);
;         __builtin_amdgcn_fence(__ATOMIC_ACQUIRE, "agent");
;         asm volatile("s_waitcnt vmcnt(0)" ::: "memory");
;     }
;     __syncthreads();
; }
; template <int LO, int HI>
; DEV void run_phases(LAS unsigned char* lds, const int ph_lo, const int ph_hi, const int G, const int wave0, unsigned& nbar) {
;     ...
;         if (ph + 1 < ph_hi) { __syncthreads(); if (HI == 1) cg::this_grid().sync(); else { ++nbar; grid_barrier((unsigned*)(ws + WS_BAR), nbar * (unsigned)G, tid); } }
.LBB0_2200:
	v_readlane_b32 s2, v251, 7
	s_add_i32 s0, s82, 1
	v_readlane_b32 s3, v251, 8
	s_cmp_ge_i32 s0, s3
	s_cbranch_scc1 .LBB0_1374
	s_waitcnt lgkmcnt(0)
	s_barrier
	s_waitcnt vmcnt(0)
	v_readlane_b32 s0, v251, 5
	s_add_i32 s0, s0, 1
	v_cmp_eq_u32_e32 vcc, 0, v131
	v_writelane_b32 v251, s0, 5
	s_barrier
	s_and_saveexec_b64 s[0:1], vcc
	s_cbranch_execz .LBB0_1373
	buffer_wbl2 sc1
	s_waitcnt vmcnt(0)
	v_readlane_b32 s2, v251, 2
	v_readlane_b32 s3, v251, 3
	v_readlane_b32 s4, v251, 1
	v_readlane_b32 s5, v251, 5
	s_getreg_b32 s6, hwreg(HW_REG_XCC_ID, 0, 4)
	s_load_dwordx2 s[2:3], s[2:3], 0x110
	s_lshr_b32 s4, s4, 3
	s_mul_i32 s4, s4, s5
	s_lshl_b32 s7, s5, 3
	s_lshl_b32 s6, s6, 2
	s_add_u32 s6, s6, 0x40
	v_mov_b32_e32 v3, 1
	v_mov_b32_e32 v2, s6
	v_mov_b32_e32 v5, 0
	s_waitcnt lgkmcnt(0)
	s_add_u32 s2, s2, 0x300000
	s_addc_u32 s3, s3, 0
	global_atomic_add v4, v2, v3, s[2:3] sc0
	s_waitcnt vmcnt(0)
	v_add_u32_e32 v4, 1, v4
	v_cmp_eq_u32_e32 vcc, s4, v4
	s_cbranch_vccz .Lgb3_follow
	global_atomic_add v5, v3, s[2:3]

; template <int LO, int HI>
; DEV void run_phases(LAS unsigned char* lds, const int ph_lo, const int ph_hi, const int G, const int wave0, unsigned& nbar) {
;     ...
;         if (ph + 1 < ph_hi) { __syncthreads(); if (HI == 1) cg::this_grid().sync(); else { ++nbar; grid_barrier((unsigned*)(ws + WS_BAR), nbar * (unsigned)G, tid); } }
;     ...
;     }
.Lgb3_done:
	s_branch .LBB0_1372
.LBB0_2206:
	s_endpgm
